# stack: GEMM1 row-stat prefetch + attention prologue rewrite + SGU su-line L2 touch prefetch at item start
# speedup vs baseline: 1.0018x; 1.0018x over previous
; __device__ __forceinline__ float bflo(unsigned u) { return __uint_as_float(u << 16); }
; __device__ __forceinline__ float bfhi(unsigned u) { return __uint_as_float(u & 0xffff0000u); }
; #define LAS __attribute__((address_space(3)))
; __device__ __forceinline__ void sgu_item(LAS unsigned char* lds, const bf16* P, bf16* Y, const float* gain, const bf16* Wsb, const float* bs, int item, int tid) {
;     const int R0 = item * 128;
;     const int g = __builtin_amdgcn_readfirstlane(tid >> 6), lane = tid & 63, fr = lane & 15, fq = lane >> 4;
;     LAS float* part = (LAS float*)lds;
;     LAS bf16* Vt = (LAS bf16*)(lds + 4096) + g * (64 * 136);
;     v4u r[2][8];
; #pragma unroll
;     for (int p = 0; p < 2; ++p) { const bf16* rp = P + (size_t)(R0 + 2 * lane + p) * PP + C_SV + g * 64;
; #pragma unroll
;         for (int c = 0; c < 8; ++c) r[p][c] = *(const v4u*)(rp + 8 * c); }
;     const bf16* Wg = Wsb + g * 16384;
; #pragma unroll
;     for (int p = 0; p < 2; ++p) { float ss = 0.f;
; #pragma unroll
;         for (int c = 0; c < 8; ++c)
; #pragma unroll
;             for (int e = 0; e < 4; ++e) { const float a0 = bflo(r[p][c][e]), a1 = bfhi(r[p][c][e]); ss += a0 * a0 + a1 * a1; }
;         part[g * 128 + 2 * lane + p] = ss; }
.LBB0_130:
	s_cmpk_gt_i32 s25, 0x1ff
	s_mov_b64 s[18:19], -1
	s_cbranch_scc0 .LBB0_132
	s_lshl_b32 s2, s25, 7
	s_add_i32 s2, s2, 0xffff0000
	v_lshrrev_b32_e32 v160, 2, v242
	v_and_b32_e32 v162, 3, v242
	v_add_u32_e32 v160, s2, v160
	v_lshlrev_b32_e32 v162, 8, v162
	v_mul_lo_u32 v160, v160, s36
	v_mov_b32_e32 v161, 0
	v_add_u32_e32 v160, v160, v162
	v_lshl_add_u64 v[160:161], v[160:161], 0, s[16:17]
	global_load_dword v162, v[160:161], off offset:1536
	global_load_dword v163, v[160:161], off offset:1664
	v_readfirstlane_b32 s18, v242
	s_ashr_i32 s3, s18, 6
	v_or_b32_e32 v0, s2, v187
	s_andn2_b32 s18, s18, 63
	s_movk_i32 s30, 0xb80
	s_ashr_i32 s19, s18, 31
	v_mul_lo_u32 v0, v0, s30
	v_mov_b32_e32 v1, v2
	v_lshl_add_u64 v[0:1], v[0:1], 1, s[16:17]
	s_lshl_b64 s[44:45], s[18:19], 1
	v_lshl_add_u64 v[0:1], v[0:1], 0, s[44:45]
	global_load_dwordx4 v[32:35], v[0:1], off offset:2608
	global_load_dwordx4 v[40:43], v[0:1], off offset:2592
	global_load_dwordx4 v[52:55], v[0:1], off offset:2576
	global_load_dwordx4 v[80:83], v[0:1], off offset:2560
	global_load_dwordx4 v[4:7], v[0:1], off offset:2672
	global_load_dwordx4 v[8:11], v[0:1], off offset:2656
	global_load_dwordx4 v[16:19], v[0:1], off offset:2640
	global_load_dwordx4 v[24:27], v[0:1], off offset:2624
	s_mov_b64 s[28:29], 0x2100
	s_movk_i32 s23, 0x2000
	v_lshl_add_u64 v[36:37], v[0:1], 0, s[28:29]
	v_add_co_u32_e32 v0, vcc, s23, v0
	v_lshl_add_u32 v3, s3, 9, v188
	s_nop 0
	v_addc_co_u32_e32 v1, vcc, 0, v1, vcc
	global_load_dwordx4 v[84:87], v[0:1], off offset:256
	global_load_dwordx4 v[44:47], v[36:37], off offset:48
	global_load_dwordx4 v[48:51], v[36:37], off offset:32
	global_load_dwordx4 v[56:59], v[36:37], off offset:16
	global_load_dwordx4 v[12:15], v[36:37], off offset:112
	global_load_dwordx4 v[20:23], v[36:37], off offset:96
	global_load_dwordx4 v[28:31], v[36:37], off offset:80
	s_nop 0
	global_load_dwordx4 v[36:39], v[36:37], off offset:64
	s_mov_b32 s28, 0x3b000000
	s_mul_i32 s22, s3, 0x4400
	s_add_i32 s22, s22, 0
	s_lshl_b32 s38, s3, 14
	s_ashr_i32 s39, s38, 31
	v_mov_b32_e32 v113, v2
	v_or_b32_e32 v232, s2, v186
	v_mov_b32_e32 v115, v2
	v_mov_b32_e32 v117, v2
	v_mov_b32_e32 v119, v2
	v_mov_b32_e32 v121, v2
	s_waitcnt vmcnt(15)
	v_lshlrev_b32_e32 v64, 16, v33
	v_and_b32_e32 v62, 0xffff0000, v33
	s_waitcnt vmcnt(12)
	v_and_b32_e32 v72, 0xffff0000, v80
	v_and_b32_e32 v76, 0xffff0000, v81
	v_lshlrev_b32_e32 v70, 16, v80
	v_lshlrev_b32_e32 v74, 16, v81
	v_and_b32_e32 v66, 0xffff0000, v82
	v_lshlrev_b32_e32 v68, 16, v82
	s_waitcnt vmcnt(7)
	v_and_b32_e32 v73, 0xffff0000, v84
	v_and_b32_e32 v77, 0xffff0000, v85
	v_lshlrev_b32_e32 v71, 16, v84
	v_lshlrev_b32_e32 v75, 16, v85
	v_pk_mul_f32 v[78:79], v[72:73], v[72:73]
	v_pk_mul_f32 v[80:81], v[76:77], v[76:77]
	v_and_b32_e32 v67, 0xffff0000, v86
	v_pk_fma_f32 v[78:79], v[70:71], v[70:71], v[78:79]
	v_pk_fma_f32 v[80:81], v[74:75], v[74:75], v[80:81]
	v_lshlrev_b32_e32 v69, 16, v86
	v_pk_add_f32 v[78:79], v[78:79], v[80:81]
	v_pk_mul_f32 v[80:81], v[66:67], v[66:67]
	s_waitcnt vmcnt(6)
	v_and_b32_e32 v33, 0xffff0000, v44
	v_pk_fma_f32 v[80:81], v[68:69], v[68:69], v[80:81]
	v_lshlrev_b32_e32 v65, 16, v45
	v_pk_add_f32 v[84:85], v[80:81], v[78:79]
	v_and_b32_e32 v81, 0xffff0000, v87
	v_and_b32_e32 v80, 0xffff0000, v83
	v_lshlrev_b32_e32 v79, 16, v87
	v_lshlrev_b32_e32 v78, 16, v83
	v_pk_mul_f32 v[82:83], v[80:81], v[80:81]
	v_and_b32_e32 v63, 0xffff0000, v45
	v_pk_fma_f32 v[82:83], v[78:79], v[78:79], v[82:83]
	v_lshlrev_b32_e32 v142, 16, v19
	v_pk_add_f32 v[86:87], v[82:83], v[84:85]
	s_waitcnt vmcnt(4)
	v_and_b32_e32 v83, 0xffff0000, v56
	v_and_b32_e32 v82, 0xffff0000, v52
	v_lshlrev_b32_e32 v84, 16, v52
	v_lshlrev_b32_e32 v85, 16, v56
	v_pk_mul_f32 v[88:89], v[82:83], v[82:83]
	v_and_b32_e32 v56, 0xffff0000, v53
	v_pk_fma_f32 v[88:89], v[84:85], v[84:85], v[88:89]
	s_waitcnt vmcnt(1)
	v_lshlrev_b32_e32 v143, 16, v31
	v_pk_add_f32 v[88:89], v[88:89], v[86:87]
	v_lshlrev_b32_e32 v87, 16, v57
	v_and_b32_e32 v57, 0xffff0000, v57
	v_lshlrev_b32_e32 v86, 16, v53
	v_pk_mul_f32 v[52:53], v[56:57], v[56:57]
	v_and_b32_e32 v31, 0xffff0000, v31
	v_pk_fma_f32 v[52:53], v[86:87], v[86:87], v[52:53]
	v_and_b32_e32 v0, 0xffff0000, v8
	v_pk_add_f32 v[90:91], v[52:53], v[88:89]
	v_and_b32_e32 v53, 0xffff0000, v58
	v_and_b32_e32 v52, 0xffff0000, v54
	v_lshlrev_b32_e32 v88, 16, v54
	v_lshlrev_b32_e32 v89, 16, v58
	v_pk_mul_f32 v[92:93], v[52:53], v[52:53]
	v_and_b32_e32 v58, 0xffff0000, v55
	v_pk_fma_f32 v[92:93], v[88:89], v[88:89], v[92:93]
	v_and_b32_e32 v1, 0xffff0000, v20
	v_pk_add_f32 v[92:93], v[92:93], v[90:91]
	v_lshlrev_b32_e32 v91, 16, v59
	v_and_b32_e32 v59, 0xffff0000, v59
	v_lshlrev_b32_e32 v90, 16, v55
	v_pk_mul_f32 v[54:55], v[58:59], v[58:59]
	v_lshlrev_b32_e32 v60, 16, v8
	v_pk_fma_f32 v[54:55], v[90:91], v[90:91], v[54:55]
	v_lshlrev_b32_e32 v61, 16, v20
	v_pk_add_f32 v[94:95], v[54:55], v[92:93]
	v_and_b32_e32 v93, 0xffff0000, v48
	v_and_b32_e32 v92, 0xffff0000, v40
	v_lshlrev_b32_e32 v54, 16, v40
	v_lshlrev_b32_e32 v55, 16, v48
	v_pk_mul_f32 v[96:97], v[92:93], v[92:93]
	v_and_b32_e32 v48, 0xffff0000, v41
	v_pk_fma_f32 v[96:97], v[54:55], v[54:55], v[96:97]
	v_and_b32_e32 v20, 0xffff0000, v9
	v_pk_add_f32 v[96:97], v[96:97], v[94:95]
	v_lshlrev_b32_e32 v95, 16, v49
	v_and_b32_e32 v49, 0xffff0000, v49
	v_lshlrev_b32_e32 v94, 16, v41
	v_pk_mul_f32 v[40:41], v[48:49], v[48:49]
	s_nop 0
	v_pk_fma_f32 v[40:41], v[94:95], v[94:95], v[40:41]
	s_nop 0
	v_pk_add_f32 v[124:125], v[40:41], v[96:97]
	v_and_b32_e32 v97, 0xffff0000, v50
	v_and_b32_e32 v96, 0xffff0000, v42
	v_lshlrev_b32_e32 v40, 16, v42
	v_lshlrev_b32_e32 v41, 16, v50
; __device__ __forceinline__ float bflo(unsigned u) { return __uint_as_float(u << 16); }
; __device__ __forceinline__ float bfhi(unsigned u) { return __uint_as_float(u & 0xffff0000u); }
; __device__ __forceinline__ void sgu_item(LAS unsigned char* lds, const bf16* P, bf16* Y, const float* gain, const bf16* Wsb, const float* bs, int item, int tid) {
;     ...
;     for (int p = 0; p < 2; ++p) { float ss = 0.f;
; #pragma unroll
;         for (int c = 0; c < 8; ++c)
; #pragma unroll
;             for (int e = 0; e < 4; ++e) { const float a0 = bflo(r[p][c][e]), a1 = bfhi(r[p][c][e]); ss += a0 * a0 + a1 * a1; }
;         part[g * 128 + 2 * lane + p] = ss; }
;     __syncthreads();
	v_pk_mul_f32 v[98:99], v[96:97], v[96:97]
	v_and_b32_e32 v50, 0xffff0000, v43
	v_pk_fma_f32 v[126:127], v[40:41], v[40:41], v[98:99]
	v_lshlrev_b32_e32 v99, 16, v51
	v_and_b32_e32 v51, 0xffff0000, v51
	v_lshlrev_b32_e32 v98, 16, v43
	v_pk_mul_f32 v[128:129], v[50:51], v[50:51]
	v_lshlrev_b32_e32 v42, 16, v32
	v_lshlrev_b32_e32 v43, 16, v44
	v_and_b32_e32 v32, 0xffff0000, v32
	v_pk_add_f32 v[44:45], v[126:127], v[124:125]
	v_pk_fma_f32 v[124:125], v[98:99], v[98:99], v[128:129]
	s_nop 0
	v_pk_add_f32 v[44:45], v[124:125], v[44:45]
	v_pk_mul_f32 v[124:125], v[32:33], v[32:33]
	s_nop 0
	v_pk_fma_f32 v[124:125], v[42:43], v[42:43], v[124:125]
	s_nop 0
	v_pk_add_f32 v[44:45], v[124:125], v[44:45]
	v_pk_mul_f32 v[124:125], v[62:63], v[62:63]
	s_nop 0
	v_pk_fma_f32 v[124:125], v[64:65], v[64:65], v[124:125]
	s_nop 0
	v_pk_add_f32 v[126:127], v[124:125], v[44:45]
	v_and_b32_e32 v125, 0xffff0000, v46
	v_and_b32_e32 v124, 0xffff0000, v34
	v_lshlrev_b32_e32 v44, 16, v34
	v_lshlrev_b32_e32 v45, 16, v46
	v_pk_mul_f32 v[128:129], v[124:125], v[124:125]
	v_and_b32_e32 v46, 0xffff0000, v35
	v_pk_fma_f32 v[128:129], v[44:45], v[44:45], v[128:129]
	s_nop 0
	v_pk_add_f32 v[128:129], v[128:129], v[126:127]
	v_lshlrev_b32_e32 v127, 16, v47
	v_and_b32_e32 v47, 0xffff0000, v47
	v_lshlrev_b32_e32 v126, 16, v35
	v_pk_mul_f32 v[34:35], v[46:47], v[46:47]
	s_nop 0
	v_pk_fma_f32 v[34:35], v[126:127], v[126:127], v[34:35]
	s_nop 0
	v_pk_add_f32 v[130:131], v[34:35], v[128:129]
	s_waitcnt vmcnt(0)
	v_and_b32_e32 v129, 0xffff0000, v36
	v_and_b32_e32 v128, 0xffff0000, v24
	v_lshlrev_b32_e32 v34, 16, v24
	v_lshlrev_b32_e32 v35, 16, v36
	v_pk_mul_f32 v[132:133], v[128:129], v[128:129]
	v_and_b32_e32 v36, 0xffff0000, v25
	v_pk_fma_f32 v[132:133], v[34:35], v[34:35], v[132:133]
	s_nop 0
	v_pk_add_f32 v[132:133], v[132:133], v[130:131]
	v_lshlrev_b32_e32 v131, 16, v37
	v_and_b32_e32 v37, 0xffff0000, v37
	v_lshlrev_b32_e32 v130, 16, v25
	v_pk_mul_f32 v[24:25], v[36:37], v[36:37]
	s_nop 0
	v_pk_fma_f32 v[24:25], v[130:131], v[130:131], v[24:25]
	s_nop 0
	v_pk_add_f32 v[134:135], v[24:25], v[132:133]
	v_and_b32_e32 v133, 0xffff0000, v38
	v_and_b32_e32 v132, 0xffff0000, v26
	v_lshlrev_b32_e32 v24, 16, v26
	v_lshlrev_b32_e32 v25, 16, v38
	v_pk_mul_f32 v[136:137], v[132:133], v[132:133]
	v_and_b32_e32 v38, 0xffff0000, v27
	v_pk_fma_f32 v[136:137], v[24:25], v[24:25], v[136:137]
	s_nop 0
	v_pk_add_f32 v[136:137], v[136:137], v[134:135]
	v_lshlrev_b32_e32 v135, 16, v39
	v_and_b32_e32 v39, 0xffff0000, v39
	v_lshlrev_b32_e32 v134, 16, v27
	v_pk_mul_f32 v[26:27], v[38:39], v[38:39]
	s_nop 0
	v_pk_fma_f32 v[26:27], v[134:135], v[134:135], v[26:27]
	s_nop 0
	v_pk_add_f32 v[138:139], v[26:27], v[136:137]
	v_and_b32_e32 v137, 0xffff0000, v28
	v_and_b32_e32 v136, 0xffff0000, v16
	v_lshlrev_b32_e32 v26, 16, v16
	v_lshlrev_b32_e32 v27, 16, v28
	v_pk_mul_f32 v[140:141], v[136:137], v[136:137]
	v_and_b32_e32 v28, 0xffff0000, v17
	v_pk_fma_f32 v[140:141], v[26:27], v[26:27], v[140:141]
	s_nop 0
	v_pk_add_f32 v[144:145], v[140:141], v[138:139]
	v_lshlrev_b32_e32 v139, 16, v29
	v_and_b32_e32 v29, 0xffff0000, v29
	v_lshlrev_b32_e32 v138, 16, v17
	v_pk_mul_f32 v[16:17], v[28:29], v[28:29]
	v_and_b32_e32 v141, 0xffff0000, v30
	v_and_b32_e32 v140, 0xffff0000, v18
	v_pk_fma_f32 v[146:147], v[138:139], v[138:139], v[16:17]
	v_lshlrev_b32_e32 v16, 16, v18
	v_lshlrev_b32_e32 v17, 16, v30
	v_pk_mul_f32 v[148:149], v[140:141], v[140:141]
	v_and_b32_e32 v30, 0xffff0000, v19
	v_pk_add_f32 v[18:19], v[146:147], v[144:145]
	v_pk_fma_f32 v[144:145], v[16:17], v[16:17], v[148:149]
	s_nop 0
	v_pk_add_f32 v[18:19], v[144:145], v[18:19]
	v_pk_mul_f32 v[144:145], v[30:31], v[30:31]
	s_nop 0
	v_pk_fma_f32 v[144:145], v[142:143], v[142:143], v[144:145]
	s_nop 0
	v_pk_add_f32 v[18:19], v[144:145], v[18:19]
	v_pk_mul_f32 v[144:145], v[0:1], v[0:1]
	s_nop 0
	v_pk_fma_f32 v[144:145], v[60:61], v[60:61], v[144:145]
	s_nop 0
	v_pk_add_f32 v[144:145], v[144:145], v[18:19]
	v_lshlrev_b32_e32 v19, 16, v21
	v_and_b32_e32 v21, 0xffff0000, v21
	v_lshlrev_b32_e32 v18, 16, v9
	v_pk_mul_f32 v[8:9], v[20:21], v[20:21]
	s_nop 0
	v_pk_fma_f32 v[8:9], v[18:19], v[18:19], v[8:9]
	s_nop 0
	v_pk_add_f32 v[146:147], v[8:9], v[144:145]
	v_and_b32_e32 v145, 0xffff0000, v22
	v_and_b32_e32 v144, 0xffff0000, v10
	v_lshlrev_b32_e32 v8, 16, v10
	v_lshlrev_b32_e32 v9, 16, v22
	v_pk_mul_f32 v[148:149], v[144:145], v[144:145]
	v_and_b32_e32 v22, 0xffff0000, v11
	v_pk_fma_f32 v[148:149], v[8:9], v[8:9], v[148:149]
	s_nop 0
	v_pk_add_f32 v[148:149], v[148:149], v[146:147]
	v_lshlrev_b32_e32 v147, 16, v23
	v_and_b32_e32 v23, 0xffff0000, v23
	v_lshlrev_b32_e32 v146, 16, v11
	v_pk_mul_f32 v[10:11], v[22:23], v[22:23]
	s_nop 0
	v_pk_fma_f32 v[10:11], v[146:147], v[146:147], v[10:11]
	s_nop 0
	v_pk_add_f32 v[150:151], v[10:11], v[148:149]
	v_and_b32_e32 v149, 0xffff0000, v12
	v_and_b32_e32 v148, 0xffff0000, v4
	v_lshlrev_b32_e32 v10, 16, v4
	v_lshlrev_b32_e32 v11, 16, v12
	v_pk_mul_f32 v[152:153], v[148:149], v[148:149]
	v_and_b32_e32 v12, 0xffff0000, v5
	v_pk_fma_f32 v[152:153], v[10:11], v[10:11], v[152:153]
	s_nop 0
	v_pk_add_f32 v[152:153], v[152:153], v[150:151]
	v_lshlrev_b32_e32 v151, 16, v13
	v_and_b32_e32 v13, 0xffff0000, v13
	v_lshlrev_b32_e32 v150, 16, v5
	v_pk_mul_f32 v[4:5], v[12:13], v[12:13]
	s_nop 0
	v_pk_fma_f32 v[4:5], v[150:151], v[150:151], v[4:5]
	s_nop 0
	v_pk_add_f32 v[154:155], v[4:5], v[152:153]
	v_and_b32_e32 v153, 0xffff0000, v14
	v_and_b32_e32 v152, 0xffff0000, v6
	v_lshlrev_b32_e32 v4, 16, v6
	v_lshlrev_b32_e32 v5, 16, v14
	v_pk_mul_f32 v[156:157], v[152:153], v[152:153]
	v_and_b32_e32 v14, 0xffff0000, v7
	v_pk_fma_f32 v[156:157], v[4:5], v[4:5], v[156:157]
	s_nop 0
	v_pk_add_f32 v[156:157], v[156:157], v[154:155]
	v_lshlrev_b32_e32 v155, 16, v15
	v_and_b32_e32 v15, 0xffff0000, v15
	v_lshlrev_b32_e32 v154, 16, v7
	v_pk_mul_f32 v[6:7], v[14:15], v[14:15]
	s_nop 0
	v_pk_fma_f32 v[6:7], v[154:155], v[154:155], v[6:7]
	s_nop 0
	v_pk_add_f32 v[6:7], v[6:7], v[156:157]
	ds_write_b64 v3, v[6:7]
	s_waitcnt lgkmcnt(0)
	s_barrier
; __device__ __forceinline__ unsigned cvt_pk_bf16(float lo, float hi) { unsigned r; asm volatile("v_cvt_pk_bf16_f32 %0, %1, %2" : "=v"(r) : "v"(lo), "v"(hi)); return r; }
; __device__ __forceinline__ float bflo(unsigned u) { return __uint_as_float(u << 16); }
; __device__ __forceinline__ float bfhi(unsigned u) { return __uint_as_float(u & 0xffff0000u); }
; #define LAS __attribute__((address_space(3)))
; __device__ __forceinline__ void sgu_item(LAS unsigned char* lds, const bf16* P, bf16* Y, const float* gain, const bf16* Wsb, const float* bs, int item, int tid) {
;     ...
;     float rs[2];
; #pragma unroll
;     for (int p = 0; p < 2; ++p) { float t = 0.f;
; #pragma unroll
;         for (int q = 0; q < 8; ++q) t += part[q * 128 + 2 * lane + p];
;         rs[p] = rsqrtf(t * (1.f / 512.f) + EPS); }
; #pragma unroll
;     for (int c = 0; c < 8; ++c)
; #pragma unroll
;         for (int e = 0; e < 4; ++e) {
;             const unsigned w0 = cvt_pk_bf16(bflo(r[0][c][e]) * rs[0], bflo(r[1][c][e]) * rs[1]), w1 = cvt_pk_bf16(bfhi(r[0][c][e]) * rs[0], bfhi(r[1][c][e]) * rs[1]);
;             *(LAS unsigned*)(Vt + (8 * c + 2 * e) * 136 + 2 * lane) = w0; *(LAS unsigned*)(Vt + (8 * c + 2 * e + 1) * 136 + 2 * lane) = w1; }
	ds_read2st64_b64 v[156:159], v188 offset1:1
	s_waitcnt lgkmcnt(0)
	v_pk_add_f32 v[6:7], v[156:157], 0 op_sel_hi:[1,0]
	s_nop 0
	v_pk_add_f32 v[6:7], v[6:7], v[158:159]
	ds_read2st64_b64 v[156:159], v188 offset0:2 offset1:3
	s_waitcnt lgkmcnt(0)
	v_pk_add_f32 v[6:7], v[6:7], v[156:157]
	s_nop 0
	v_pk_add_f32 v[6:7], v[6:7], v[158:159]
	ds_read2st64_b64 v[156:159], v188 offset0:4 offset1:5
	s_waitcnt lgkmcnt(0)
	v_pk_add_f32 v[6:7], v[6:7], v[156:157]
	s_nop 0
	v_pk_add_f32 v[6:7], v[6:7], v[158:159]
	ds_read2st64_b64 v[156:159], v188 offset0:6 offset1:7
	s_waitcnt lgkmcnt(0)
	v_pk_add_f32 v[6:7], v[6:7], v[156:157]
	s_nop 0
	v_pk_add_f32 v[6:7], v[6:7], v[158:159]
	s_nop 0
	v_pk_fma_f32 v[6:7], v[6:7], s[28:29], v[196:197] op_sel_hi:[1,0,0]
	s_nop 0
	v_mul_f32_e32 v3, 0x4b800000, v6
	v_cmp_gt_f32_e64 s[62:63], s13, v6
	v_cmp_gt_f32_e32 vcc, s13, v7
	s_nop 0
	v_cndmask_b32_e64 v3, v6, v3, s[62:63]
	v_rsq_f32_e32 v3, v3
	s_nop 0
	v_mul_f32_e32 v6, 0x45800000, v3
	v_cndmask_b32_e64 v3, v3, v6, s[62:63]
	v_mul_f32_e32 v6, 0x4b800000, v7
	v_cndmask_b32_e32 v6, v7, v6, vcc
	v_rsq_f32_e32 v6, v6
	v_mul_f32_e32 v66, v3, v66
	v_mul_f32_e32 v56, v3, v56
	v_mul_f32_e32 v52, v3, v52
	v_mul_f32_e32 v7, 0x45800000, v6
	v_cndmask_b32_e32 v6, v6, v7, vcc
	v_mul_f32_e32 v7, v3, v70
	v_mul_f32_e32 v70, v6, v71
	v_cvt_pk_bf16_f32 v7, v7, v70
	v_mul_f32_e32 v70, v3, v72
	v_mul_f32_e32 v71, v6, v73
	v_cvt_pk_bf16_f32 v70, v70, v71
	v_lshl_add_u32 v71, v187, 1, s22
	v_add_u32_e32 v72, 0x1000, v71
	ds_write2_b32 v72, v7, v70 offset1:68
	v_mul_f32_e32 v7, v3, v74
	v_mul_f32_e32 v70, v6, v75
	v_cvt_pk_bf16_f32 v7, v7, v70
	v_mul_f32_e32 v70, v3, v76
	v_mul_f32_e32 v73, v6, v77
	v_cvt_pk_bf16_f32 v70, v70, v73
	ds_write2_b32 v72, v7, v70 offset0:136 offset1:204
	v_mul_f32_e32 v7, v3, v68
	v_mul_f32_e32 v67, v6, v67
	v_mul_f32_e32 v68, v6, v69
	v_cvt_pk_bf16_f32 v7, v7, v68
	v_cvt_pk_bf16_f32 v66, v66, v67
	v_add_u32_e32 v67, 0x1400, v71
	ds_write2_b32 v67, v7, v66 offset0:16 offset1:84
	v_mul_f32_e32 v7, v3, v78
	v_mul_f32_e32 v66, v6, v79
	v_cvt_pk_bf16_f32 v7, v7, v66
	v_mul_f32_e32 v66, v3, v80
	v_mul_f32_e32 v68, v6, v81
	v_cvt_pk_bf16_f32 v66, v66, v68
	ds_write2_b32 v67, v7, v66 offset0:152 offset1:220
	v_mul_f32_e32 v7, v3, v84
	v_mul_f32_e32 v66, v6, v85
	v_cvt_pk_bf16_f32 v7, v7, v66
	v_mul_f32_e32 v66, v3, v82
	v_mul_f32_e32 v67, v6, v83
	v_cvt_pk_bf16_f32 v66, v66, v67
	v_add_u32_e32 v67, 0x1800, v71
	ds_write2_b32 v67, v7, v66 offset0:32 offset1:100
	v_mul_f32_e32 v7, v3, v86
	v_mul_f32_e32 v66, v6, v87
	v_cvt_pk_bf16_f32 v7, v7, v66
	v_mul_f32_e32 v57, v6, v57
	v_cvt_pk_bf16_f32 v56, v56, v57
	ds_write2_b32 v67, v7, v56 offset0:168 offset1:236
	v_mul_f32_e32 v7, v3, v88
	v_mul_f32_e32 v53, v6, v53
	v_mul_f32_e32 v56, v6, v89
	v_cvt_pk_bf16_f32 v7, v7, v56
	v_cvt_pk_bf16_f32 v52, v52, v53
	v_add_u32_e32 v53, 0x1c00, v71
	ds_write2_b32 v53, v7, v52 offset0:48 offset1:116
	v_mul_f32_e32 v7, v3, v90
	v_mul_f32_e32 v52, v6, v91
	v_cvt_pk_bf16_f32 v7, v7, v52
	v_mul_f32_e32 v52, v3, v58
	v_mul_f32_e32 v56, v6, v59
	v_cvt_pk_bf16_f32 v52, v52, v56
	ds_write2_b32 v53, v7, v52 offset0:184 offset1:252
	v_mul_f32_e32 v7, v3, v54
	v_mul_f32_e32 v52, v6, v55
	v_cvt_pk_bf16_f32 v7, v7, v52
	v_mul_f32_e32 v52, v3, v92
	v_mul_f32_e32 v53, v6, v93
	v_cvt_pk_bf16_f32 v52, v52, v53
	v_add_u32_e32 v53, 0x2000, v71
	ds_write2_b32 v53, v7, v52 offset0:64 offset1:132
	v_mul_f32_e32 v7, v3, v94
	v_mul_f32_e32 v48, v3, v48
	v_mul_f32_e32 v49, v6, v49
	v_mul_f32_e32 v52, v6, v95
	v_cvt_pk_bf16_f32 v7, v7, v52
	v_cvt_pk_bf16_f32 v48, v48, v49
	v_add_u32_e32 v49, 0x2200, v71
	ds_write2_b32 v49, v7, v48 offset0:72 offset1:140
	v_mul_f32_e32 v7, v3, v40
	v_mul_f32_e32 v40, v6, v41
	v_cvt_pk_bf16_f32 v7, v7, v40
	v_mul_f32_e32 v40, v3, v96
	v_mul_f32_e32 v41, v6, v97
	v_cvt_pk_bf16_f32 v40, v40, v41
	v_add_u32_e32 v41, 0x2400, v71
	ds_write2_b32 v41, v7, v40 offset0:80 offset1:148
	v_mul_f32_e32 v7, v3, v98
	v_mul_f32_e32 v40, v6, v99
	v_cvt_pk_bf16_f32 v7, v7, v40
	v_mul_f32_e32 v40, v3, v50
	v_mul_f32_e32 v41, v6, v51
	v_cvt_pk_bf16_f32 v40, v40, v41
	v_add_u32_e32 v41, 0x2600, v71
	ds_write2_b32 v41, v7, v40 offset0:88 offset1:156
	v_mul_f32_e32 v7, v3, v42
	v_mul_f32_e32 v32, v3, v32
	v_mul_f32_e32 v33, v6, v33
	v_mul_f32_e32 v40, v6, v43
	v_cvt_pk_bf16_f32 v7, v7, v40
	v_cvt_pk_bf16_f32 v32, v32, v33
	v_add_u32_e32 v33, 0x2800, v71
	ds_write2_b32 v33, v7, v32 offset0:96 offset1:164
	v_mul_f32_e32 v7, v3, v64
	v_mul_f32_e32 v32, v6, v65
	v_cvt_pk_bf16_f32 v7, v7, v32
	v_mul_f32_e32 v32, v3, v62
	v_mul_f32_e32 v33, v6, v63
	v_cvt_pk_bf16_f32 v32, v32, v33
	v_add_u32_e32 v33, 0x2a00, v71
	ds_write2_b32 v33, v7, v32 offset0:104 offset1:172
	v_mul_f32_e32 v7, v3, v44
	v_mul_f32_e32 v32, v6, v45
	v_cvt_pk_bf16_f32 v7, v7, v32
	v_mul_f32_e32 v32, v3, v124
	v_mul_f32_e32 v33, v6, v125
	v_cvt_pk_bf16_f32 v32, v32, v33
	v_add_u32_e32 v33, 0x2c00, v71
	ds_write2_b32 v33, v7, v32 offset0:112 offset1:180
	v_mul_f32_e32 v7, v3, v126
	v_mul_f32_e32 v32, v6, v127
	v_cvt_pk_bf16_f32 v7, v7, v32
	v_mul_f32_e32 v32, v3, v46
	v_mul_f32_e32 v33, v6, v47
	v_cvt_pk_bf16_f32 v32, v32, v33
	v_add_u32_e32 v33, 0x2e00, v71
	ds_write2_b32 v33, v7, v32 offset0:120 offset1:188
	v_mul_f32_e32 v7, v3, v34
	v_mul_f32_e32 v32, v6, v35
	v_cvt_pk_bf16_f32 v7, v7, v32
	v_mul_f32_e32 v32, v3, v128
	v_mul_f32_e32 v33, v6, v129
	v_cvt_pk_bf16_f32 v32, v32, v33
	v_add_u32_e32 v33, 0x3000, v71
	ds_write2_b32 v33, v7, v32 offset0:128 offset1:196
	v_mul_f32_e32 v7, v3, v130
	v_mul_f32_e32 v32, v6, v131
	v_cvt_pk_bf16_f32 v7, v7, v32
	v_mul_f32_e32 v32, v3, v36
	v_mul_f32_e32 v33, v6, v37
	v_cvt_pk_bf16_f32 v32, v32, v33
; #define LAS __attribute__((address_space(3)))
; __device__ __forceinline__ void sgu_item(LAS unsigned char* lds, const bf16* P, bf16* Y, const float* gain, const bf16* Wsb, const float* bs, int item, int tid) {
;     ...
;             *(LAS unsigned*)(Vt + (8 * c + 2 * e) * 136 + 2 * lane) = w0; *(LAS unsigned*)(Vt + (8 * c + 2 * e + 1) * 136 + 2 * lane) = w1; }
;     f32x4 gn[4];
; #pragma unroll
;     for (int db = 0; db < 4; ++db) gn[db] = *(const f32x4*)(gain + g * 64 + 16 * db + 4 * fq);
;     __syncthreads();
;     bf16x8 wfr[8][4]; v2u sur[8][4]; float bia[8];
; #pragma unroll
;     for (int ib = 0; ib < 8; ++ib) { const bf16* wp = Wg + (16 * ib + fr) * 128 + 8 * fq;
; #pragma unroll
;         for (int ks = 0; ks < 4; ++ks) if (ks <= (ib >> 1)) wfr[ib][ks] = *(const bf16x8*)(wp + 32 * ks);
;         const bf16* up = P + (size_t)(R0 + 16 * ib + fr) * PP + C_SU + g * 64 + 4 * fq;
; #pragma unroll
;         for (int db = 0; db < 4; ++db) sur[ib][db] = *(const v2u*)(up + 16 * db);
;         bia[ib] = bs[g * 128 + 16 * ib + fr]; }
	v_add_u32_e32 v33, 0x3400, v71
	ds_write2_b32 v33, v7, v32 offset0:8 offset1:76
	v_mul_f32_e32 v7, v3, v24
	v_mul_f32_e32 v24, v6, v25
	v_cvt_pk_bf16_f32 v7, v7, v24
	v_mul_f32_e32 v24, v3, v132
	v_mul_f32_e32 v25, v6, v133
	v_cvt_pk_bf16_f32 v24, v24, v25
	ds_write2_b32 v33, v7, v24 offset0:144 offset1:212
	v_mul_f32_e32 v7, v3, v134
	v_mul_f32_e32 v24, v6, v135
	v_cvt_pk_bf16_f32 v7, v7, v24
	v_mul_f32_e32 v24, v3, v38
	v_mul_f32_e32 v25, v6, v39
	v_cvt_pk_bf16_f32 v24, v24, v25
	v_add_u32_e32 v25, 0x3800, v71
	ds_write2_b32 v25, v7, v24 offset0:24 offset1:92
	v_mul_f32_e32 v7, v3, v26
	v_mul_f32_e32 v24, v6, v27
	v_cvt_pk_bf16_f32 v7, v7, v24
	v_mul_f32_e32 v24, v3, v136
	v_mul_f32_e32 v26, v6, v137
	v_cvt_pk_bf16_f32 v24, v24, v26
	ds_write2_b32 v25, v7, v24 offset0:160 offset1:228
	v_mul_f32_e32 v7, v3, v138
	v_mul_f32_e32 v24, v6, v139
	v_cvt_pk_bf16_f32 v7, v7, v24
	v_mul_f32_e32 v24, v3, v28
	v_mul_f32_e32 v25, v6, v29
	v_cvt_pk_bf16_f32 v24, v24, v25
	v_add_u32_e32 v25, 0x3c00, v71
	ds_write2_b32 v25, v7, v24 offset0:40 offset1:108
	v_mul_f32_e32 v7, v3, v16
	v_mul_f32_e32 v16, v6, v17
	v_cvt_pk_bf16_f32 v7, v7, v16
	v_mul_f32_e32 v16, v3, v140
	v_mul_f32_e32 v17, v6, v141
	v_cvt_pk_bf16_f32 v16, v16, v17
	ds_write2_b32 v25, v7, v16 offset0:176 offset1:244
	v_mul_f32_e32 v7, v3, v142
	v_mul_f32_e32 v16, v6, v143
	v_cvt_pk_bf16_f32 v7, v7, v16
	v_mul_f32_e32 v16, v3, v30
	v_mul_f32_e32 v17, v6, v31
	v_cvt_pk_bf16_f32 v16, v16, v17
	v_add_u32_e32 v17, 0x4000, v71
	ds_write2_b32 v17, v7, v16 offset0:56 offset1:124
	v_mul_f32_e32 v7, v3, v60
	v_mul_f32_e32 v0, v3, v0
	v_mul_f32_e32 v1, v6, v1
	v_mul_f32_e32 v16, v6, v61
	v_cvt_pk_bf16_f32 v7, v7, v16
	v_cvt_pk_bf16_f32 v0, v0, v1
	v_add_u32_e32 v1, 0x4200, v71
	ds_write2_b32 v1, v7, v0 offset0:64 offset1:132
	v_mul_f32_e32 v0, v3, v18
	v_mul_f32_e32 v1, v6, v19
	v_cvt_pk_bf16_f32 v0, v0, v1
	v_mul_f32_e32 v1, v3, v20
	v_mul_f32_e32 v7, v6, v21
	v_cvt_pk_bf16_f32 v1, v1, v7
	v_add_u32_e32 v7, 0x4400, v71
	ds_write2_b32 v7, v0, v1 offset0:72 offset1:140
	v_mul_f32_e32 v0, v3, v8
	v_mul_f32_e32 v1, v6, v9
	v_cvt_pk_bf16_f32 v0, v0, v1
	v_mul_f32_e32 v1, v3, v144
	v_mul_f32_e32 v7, v6, v145
	v_cvt_pk_bf16_f32 v1, v1, v7
	v_add_u32_e32 v7, 0x4600, v71
	ds_write2_b32 v7, v0, v1 offset0:80 offset1:148
	v_mul_f32_e32 v0, v3, v146
	v_mul_f32_e32 v1, v6, v147
	v_cvt_pk_bf16_f32 v0, v0, v1
	v_mul_f32_e32 v1, v3, v22
	v_mul_f32_e32 v7, v6, v23
	v_cvt_pk_bf16_f32 v1, v1, v7
	v_add_u32_e32 v7, 0x4800, v71
	ds_write2_b32 v7, v0, v1 offset0:88 offset1:156
	v_mul_f32_e32 v0, v3, v10
	v_mul_f32_e32 v1, v6, v11
	v_cvt_pk_bf16_f32 v0, v0, v1
	v_mul_f32_e32 v1, v3, v148
	v_mul_f32_e32 v7, v6, v149
	v_cvt_pk_bf16_f32 v1, v1, v7
	v_add_u32_e32 v7, 0x4a00, v71
	ds_write2_b32 v7, v0, v1 offset0:96 offset1:164
	v_mul_f32_e32 v0, v3, v150
	v_mul_f32_e32 v1, v6, v151
	v_cvt_pk_bf16_f32 v0, v0, v1
	v_mul_f32_e32 v1, v3, v12
	v_mul_f32_e32 v7, v6, v13
	v_cvt_pk_bf16_f32 v1, v1, v7
	v_add_u32_e32 v7, 0x4c00, v71
	ds_write2_b32 v7, v0, v1 offset0:104 offset1:172
	v_mul_f32_e32 v0, v3, v4
	v_mul_f32_e32 v1, v6, v5
	v_cvt_pk_bf16_f32 v0, v0, v1
	v_mul_f32_e32 v1, v3, v152
	v_mul_f32_e32 v4, v6, v153
	v_cvt_pk_bf16_f32 v1, v1, v4
	v_add_u32_e32 v4, 0x4e00, v71
	ds_write2_b32 v4, v0, v1 offset0:112 offset1:180
	v_mul_f32_e32 v0, v3, v154
	v_mul_f32_e32 v1, v6, v155
	v_cvt_pk_bf16_f32 v0, v0, v1
	v_mul_f32_e32 v1, v3, v14
	v_mul_f32_e32 v3, v6, v15
	v_cvt_pk_bf16_f32 v1, v1, v3
	v_add_u32_e32 v3, 0x5000, v71
	ds_write2_b32 v3, v0, v1 offset0:120 offset1:188
	v_lshl_add_u64 v[0:1], s[18:19], 2, v[100:101]
	global_load_dwordx4 v[16:19], v[0:1], off
	global_load_dwordx4 v[12:15], v[0:1], off offset:64
	global_load_dwordx4 v[8:11], v[0:1], off offset:128
	global_load_dwordx4 v[4:7], v[0:1], off offset:192
	v_lshl_add_u64 v[0:1], s[38:39], 1, v[102:103]
	v_lshl_add_u64 v[22:23], v[0:1], 0, v[112:113]
	s_waitcnt lgkmcnt(0)
	s_barrier
	global_load_dwordx4 v[96:99], v[22:23], off
	v_mul_lo_u32 v24, v232, s30
	v_mov_b32_e32 v25, v2
	v_lshl_or_b32 v20, s3, 7, v186
	v_lshl_add_u64 v[24:25], v[24:25], 1, s[16:17]
	v_lshl_add_u64 v[24:25], v[24:25], 0, s[44:45]
	v_ashrrev_i32_e32 v21, 31, v20
	v_lshl_add_u64 v[124:125], v[24:25], 0, v[114:115]
	v_lshl_add_u64 v[224:225], v[20:21], 2, s[40:41]
	global_load_dwordx2 v[184:185], v[124:125], off offset:1536
	global_load_dwordx2 v[182:183], v[124:125], off offset:1568
	global_load_dwordx2 v[180:181], v[124:125], off offset:1600
	global_load_dwordx2 v[178:179], v[124:125], off offset:1632
	global_load_dword v233, v[224:225], off
	v_lshl_add_u64 v[20:21], v[0:1], 0, v[116:117]
	global_load_dwordx4 v[92:95], v[20:21], off
	s_mov_b64 s[2:3], 0x17600
	v_lshl_add_u64 v[20:21], v[124:125], 0, s[2:3]
	s_mov_b32 s2, 0x17000
	v_add_co_u32_e32 v24, vcc, s2, v124
	s_mov_b64 s[2:3], 0x2e600
	s_nop 0
	v_addc_co_u32_e32 v25, vcc, 0, v125, vcc
	global_load_dwordx2 v[176:177], v[24:25], off offset:1536
	global_load_dwordx2 v[174:175], v[20:21], off offset:32
	global_load_dwordx2 v[172:173], v[20:21], off offset:64
	global_load_dwordx2 v[170:171], v[20:21], off offset:96
	global_load_dword v243, v[224:225], off offset:64
	v_lshl_add_u64 v[20:21], v[0:1], 0, v[118:119]
	global_load_dwordx4 v[88:91], v[20:21], off
	global_load_dwordx4 v[84:87], v[20:21], off offset:64
	v_lshl_add_u64 v[20:21], v[124:125], 0, s[2:3]
	s_mov_b32 s2, 0x2e000
	v_add_co_u32_e32 v24, vcc, s2, v124
	v_lshl_add_u64 v[0:1], v[0:1], 0, v[120:121]
	s_nop 0
	v_addc_co_u32_e32 v25, vcc, 0, v125, vcc
	s_mov_b64 s[2:3], 0x45600
	global_load_dwordx2 v[168:169], v[24:25], off offset:1536
	global_load_dwordx2 v[166:167], v[20:21], off offset:32
; #define LAS __attribute__((address_space(3)))
; __device__ __forceinline__ void sgu_item(LAS unsigned char* lds, const bf16* P, bf16* Y, const float* gain, const bf16* Wsb, const float* bs, int item, int tid) {
;     ...
; #pragma unroll
;     for (int ib = 0; ib < 8; ++ib) { const bf16* wp = Wg + (16 * ib + fr) * 128 + 8 * fq;
; #pragma unroll
;         for (int ks = 0; ks < 4; ++ks) if (ks <= (ib >> 1)) wfr[ib][ks] = *(const bf16x8*)(wp + 32 * ks);
;         const bf16* up = P + (size_t)(R0 + 16 * ib + fr) * PP + C_SU + g * 64 + 4 * fq;
; #pragma unroll
;         for (int db = 0; db < 4; ++db) sur[ib][db] = *(const v2u*)(up + 16 * db);
;         bia[ib] = bs[g * 128 + 16 * ib + fr]; }
; #pragma unroll
;     for (int ib = 0; ib < 8; ++ib) {
;         f32x4 acc[4];
; #pragma unroll
;         for (int db = 0; db < 4; ++db) acc[db] = (f32x4){0.f, 0.f, 0.f, 0.f};
; #pragma unroll
;         for (int ks = 0; ks < 4; ++ks) if (ks <= (ib >> 1)) {
; #pragma unroll
;             for (int db = 0; db < 4; ++db) { const bf16x8 vf = *(const LAS bf16x8*)(Vt + (16 * db + fr) * 136 + 32 * ks + 8 * fq); acc[db] = __builtin_amdgcn_mfma_f32_16x16x32_bf16(vf, wfr[ib][ks], acc[db], 0, 0, 0); } }
;         bf16* yp = Y + (size_t)(R0 + 16 * ib + fr) * D + 512 + g * 64 + 4 * fq; const float bias = bia[ib];
	global_load_dwordx2 v[164:165], v[20:21], off offset:64
	global_load_dwordx2 v[162:163], v[20:21], off offset:96
	global_load_dword v223, v[224:225], off offset:128
	global_load_dwordx4 v[80:83], v[0:1], off
	global_load_dwordx4 v[76:79], v[0:1], off offset:64
	v_lshl_add_u64 v[0:1], v[124:125], 0, s[2:3]
	s_mov_b32 s2, 0x45000
	v_add_co_u32_e32 v20, vcc, s2, v124
	s_movk_i32 s2, 0x4000
	s_nop 0
	v_addc_co_u32_e32 v21, vcc, 0, v125, vcc
	global_load_dwordx2 v[160:161], v[20:21], off offset:1536
	global_load_dwordx2 v[158:159], v[0:1], off offset:32
	global_load_dwordx2 v[156:157], v[0:1], off offset:64
	global_load_dwordx2 v[154:155], v[0:1], off offset:96
	global_load_dword v123, v[224:225], off offset:192
	v_add_co_u32_e32 v0, vcc, s2, v22
	s_movk_i32 s2, 0x5000
	s_nop 0
	v_addc_co_u32_e32 v1, vcc, 0, v23, vcc
	v_add_co_u32_e32 v20, vcc, s2, v22
	s_mov_b64 s[2:3], 0x5c600
	s_nop 0
	v_addc_co_u32_e32 v21, vcc, 0, v23, vcc
	global_load_dwordx4 v[72:75], v[20:21], off offset:-4096
	global_load_dwordx4 v[68:71], v[0:1], off offset:64
	global_load_dwordx4 v[64:67], v[0:1], off offset:128
	v_lshl_add_u64 v[0:1], v[124:125], 0, s[2:3]
	s_mov_b32 s2, 0x5c000
	v_add_co_u32_e32 v24, vcc, s2, v124
	s_mov_b64 s[2:3], 0x73600
	s_nop 0
	v_addc_co_u32_e32 v25, vcc, 0, v125, vcc
	global_load_dwordx2 v[152:153], v[24:25], off offset:1536
	global_load_dwordx2 v[150:151], v[0:1], off offset:32
	global_load_dwordx2 v[148:149], v[0:1], off offset:64
	global_load_dwordx2 v[146:147], v[0:1], off offset:96
	global_load_dword v121, v[224:225], off offset:256
	global_load_dwordx4 v[60:63], v[20:21], off
	global_load_dwordx4 v[56:59], v[20:21], off offset:64
	global_load_dwordx4 v[52:55], v[20:21], off offset:128
	v_lshl_add_u64 v[0:1], v[124:125], 0, s[2:3]
	s_mov_b32 s2, 0x73000
	v_add_co_u32_e32 v20, vcc, s2, v124
	s_movk_i32 s2, 0x6000
	s_nop 0
	v_addc_co_u32_e32 v21, vcc, 0, v125, vcc
	global_load_dwordx2 v[144:145], v[20:21], off offset:1536
	global_load_dwordx2 v[142:143], v[0:1], off offset:32
	global_load_dwordx2 v[140:141], v[0:1], off offset:64
	global_load_dwordx2 v[138:139], v[0:1], off offset:96
	global_load_dword v119, v[224:225], off offset:320
	v_add_co_u32_e32 v0, vcc, s2, v22
	s_movk_i32 s2, 0x7000
	s_nop 0
	v_addc_co_u32_e32 v1, vcc, 0, v23, vcc
	v_add_co_u32_e32 v20, vcc, s2, v22
	s_mov_b64 s[2:3], 0x8a600
	s_nop 0
	v_addc_co_u32_e32 v21, vcc, 0, v23, vcc
	global_load_dwordx4 v[48:51], v[20:21], off offset:-4096
	global_load_dwordx4 v[44:47], v[0:1], off offset:64
	global_load_dwordx4 v[40:43], v[0:1], off offset:128
	global_load_dwordx4 v[36:39], v[0:1], off offset:192
	v_lshl_add_u64 v[0:1], v[124:125], 0, s[2:3]
	s_mov_b32 s2, 0x8a000
	v_add_co_u32_e32 v22, vcc, s2, v124
	s_mov_b64 s[2:3], 0xa1600
	s_nop 0
	v_addc_co_u32_e32 v23, vcc, 0, v125, vcc
	global_load_dwordx2 v[136:137], v[22:23], off offset:1536
	global_load_dwordx2 v[134:135], v[0:1], off offset:32
	global_load_dwordx2 v[132:133], v[0:1], off offset:64
	global_load_dwordx2 v[130:131], v[0:1], off offset:96
	global_load_dword v117, v[224:225], off offset:384
	global_load_dwordx4 v[32:35], v[20:21], off
	global_load_dwordx4 v[28:31], v[20:21], off offset:64
	global_load_dwordx4 v[24:27], v[20:21], off offset:128
	s_nop 0
	global_load_dwordx4 v[20:23], v[20:21], off offset:192
	v_lshl_add_u64 v[0:1], v[124:125], 0, s[2:3]
	s_mov_b32 s2, 0xa1000
	v_add_co_u32_e32 v124, vcc, s2, v124
	v_add3_u32 v113, s22, v189, v190
	s_nop 0
	v_addc_co_u32_e32 v125, vcc, 0, v125, vcc
	global_load_dwordx2 v[128:129], v[124:125], off offset:1536
	global_load_dwordx2 v[126:127], v[0:1], off offset:32
	s_nop 0
	global_load_dwordx2 v[124:125], v[0:1], off offset:64
	s_nop 0
	global_load_dwordx2 v[0:1], v[0:1], off offset:96
	s_nop 0
	global_load_dword v3, v[224:225], off offset:448
	ds_read_b128 v[224:227], v113 offset:4096
	ds_read_b128 v[228:231], v113 offset:8448
	ds_read_b128 v[244:247], v113 offset:12800
	ds_read_b128 v[248:251], v113 offset:17152
	s_waitcnt vmcnt(59) lgkmcnt(3)
	v_mfma_f32_16x16x32_bf16 v[224:227], v[224:227], v[96:99], 0
	s_mov_b64 s[2:3], 0x8400
	s_mov_b64 s[18:19], 0
	s_waitcnt lgkmcnt(2)
	v_mfma_f32_16x16x32_bf16 v[228:231], v[228:231], v[96:99], 0
	s_waitcnt lgkmcnt(1)
	v_mfma_f32_16x16x32_bf16 v[244:247], v[244:247], v[96:99], 0
	s_waitcnt lgkmcnt(0)
	v_mfma_f32_16x16x32_bf16 v[248:251], v[248:251], v[96:99], 0
	v_lshlrev_b32_e32 v96, 11, v232
	v_mov_b32_e32 v97, v2
	v_lshl_add_u64 v[96:97], s[14:15], 0, v[96:97]
	v_lshl_add_u64 v[96:97], v[96:97], 0, s[44:45]
	s_waitcnt vmcnt(58)
	v_lshlrev_b32_e32 v98, 16, v184
	s_waitcnt vmcnt(54)
; __device__ __forceinline__ unsigned cvt_pk_bf16(float lo, float hi) { unsigned r; asm volatile("v_cvt_pk_bf16_f32 %0, %1, %2" : "=v"(r) : "v"(lo), "v"(hi)); return r; }
; __device__ __forceinline__ float bflo(unsigned u) { return __uint_as_float(u << 16); }
; __device__ __forceinline__ float bfhi(unsigned u) { return __uint_as_float(u & 0xffff0000u); }
; #define LAS __attribute__((address_space(3)))
; __device__ __forceinline__ void sgu_item(LAS unsigned char* lds, const bf16* P, bf16* Y, const float* gain, const bf16* Wsb, const float* bs, int item, int tid) {
;     ...
; #pragma unroll
;     for (int ib = 0; ib < 8; ++ib) {
;         f32x4 acc[4];
; #pragma unroll
;         for (int db = 0; db < 4; ++db) acc[db] = (f32x4){0.f, 0.f, 0.f, 0.f};
; #pragma unroll
;         for (int ks = 0; ks < 4; ++ks) if (ks <= (ib >> 1)) {
; #pragma unroll
;             for (int db = 0; db < 4; ++db) { const bf16x8 vf = *(const LAS bf16x8*)(Vt + (16 * db + fr) * 136 + 32 * ks + 8 * fq); acc[db] = __builtin_amdgcn_mfma_f32_16x16x32_bf16(vf, wfr[ib][ks], acc[db], 0, 0, 0); } }
;         bf16* yp = Y + (size_t)(R0 + 16 * ib + fr) * D + 512 + g * 64 + 4 * fq; const float bias = bia[ib];
; #pragma unroll
;         for (int db = 0; db < 4; ++db) {
;             v2u wv; wv.x = cvt_pk_bf16(bflo(sur[ib][db].x) * (acc[db][0] * gn[db][0] + bias), bfhi(sur[ib][db].x) * (acc[db][1] * gn[db][1] + bias));
;             wv.y = cvt_pk_bf16(bflo(sur[ib][db].y) * (acc[db][2] * gn[db][2] + bias), bfhi(sur[ib][db].y) * (acc[db][3] * gn[db][3] + bias));
;             *(v2u*)(yp + 16 * db) = wv; }
	v_fma_f32 v99, v16, v224, v233
	v_lshl_add_u64 v[96:97], v[96:97], 0, v[114:115]
	v_mul_f32_e32 v98, v99, v98
	v_and_b32_e32 v99, 0xffff0000, v184
	v_fma_f32 v115, v17, v225, v233
	v_mul_f32_e32 v99, v115, v99
	v_cvt_pk_bf16_f32 v98, v98, v99
	v_lshlrev_b32_e32 v99, 16, v185
	v_fma_f32 v115, v18, v226, v233
	v_mul_f32_e32 v99, v115, v99
	v_and_b32_e32 v115, 0xffff0000, v185
	v_fma_f32 v184, v19, v227, v233
	v_mul_f32_e32 v115, v184, v115
	v_cvt_pk_bf16_f32 v99, v99, v115
	global_store_dwordx2 v[96:97], v[98:99], off offset:1024
	v_lshlrev_b32_e32 v98, 16, v182
	v_fma_f32 v99, v12, v228, v233
	v_mul_f32_e32 v98, v99, v98
	v_and_b32_e32 v99, 0xffff0000, v182
	v_fma_f32 v115, v13, v229, v233
	v_mul_f32_e32 v99, v115, v99
	v_cvt_pk_bf16_f32 v98, v98, v99
	v_lshlrev_b32_e32 v99, 16, v183
	v_fma_f32 v115, v14, v230, v233
	v_mul_f32_e32 v99, v115, v99
	v_and_b32_e32 v115, 0xffff0000, v183
	v_fma_f32 v182, v15, v231, v233
	v_mul_f32_e32 v115, v182, v115
	v_cvt_pk_bf16_f32 v99, v99, v115
	global_store_dwordx2 v[96:97], v[98:99], off offset:1056
	v_lshlrev_b32_e32 v98, 16, v180
	v_fma_f32 v99, v8, v244, v233
	v_mul_f32_e32 v98, v99, v98
	v_and_b32_e32 v99, 0xffff0000, v180
	v_fma_f32 v115, v9, v245, v233
	v_mul_f32_e32 v99, v115, v99
	v_cvt_pk_bf16_f32 v98, v98, v99
	v_lshlrev_b32_e32 v99, 16, v181
	v_fma_f32 v115, v10, v246, v233
	v_mul_f32_e32 v99, v115, v99
	v_and_b32_e32 v115, 0xffff0000, v181
	v_fma_f32 v180, v11, v247, v233
	v_mul_f32_e32 v115, v180, v115
	v_cvt_pk_bf16_f32 v99, v99, v115
	global_store_dwordx2 v[96:97], v[98:99], off offset:1088
	v_lshlrev_b32_e32 v98, 16, v178
	v_fma_f32 v99, v4, v248, v233
	v_mul_f32_e32 v98, v99, v98
	v_and_b32_e32 v99, 0xffff0000, v178
	v_fma_f32 v115, v5, v249, v233
	v_mul_f32_e32 v99, v115, v99
	v_cvt_pk_bf16_f32 v98, v98, v99
	v_lshlrev_b32_e32 v99, 16, v179
	v_fma_f32 v115, v6, v250, v233
	v_mul_f32_e32 v99, v115, v99
	v_and_b32_e32 v115, 0xffff0000, v179
	v_fmac_f32_e32 v233, v7, v251
	v_mul_f32_e32 v115, v233, v115
	v_cvt_pk_bf16_f32 v99, v99, v115
	ds_read_b128 v[178:181], v113 offset:4096
	ds_read_b128 v[182:185], v113 offset:8448
	s_waitcnt vmcnt(56) lgkmcnt(1)
	v_mfma_f32_16x16x32_bf16 v[178:181], v[178:181], v[92:95], 0
	ds_read_b128 v[224:227], v113 offset:12800
	ds_read_b128 v[228:231], v113 offset:17152
	s_waitcnt vmcnt(55)
	v_lshlrev_b32_e32 v115, 16, v176
	s_waitcnt vmcnt(51)
	s_nop 2
	v_fma_f32 v178, v16, v178, v243
	v_mul_f32_e32 v115, v178, v115
	v_and_b32_e32 v176, 0xffff0000, v176
	v_fma_f32 v178, v17, v179, v243
	v_mul_f32_e32 v176, v178, v176
	global_store_dwordx2 v[96:97], v[98:99], off offset:1120
	s_waitcnt lgkmcnt(2)
	v_mfma_f32_16x16x32_bf16 v[182:185], v[182:185], v[92:95], 0
	v_cvt_pk_bf16_f32 v176, v115, v176
	v_lshlrev_b32_e32 v115, 16, v177
	v_fma_f32 v178, v18, v180, v243
	v_lshl_add_u64 v[98:99], v[96:97], 0, s[2:3]
	v_mul_f32_e32 v115, v178, v115
	v_and_b32_e32 v177, 0xffff0000, v177
	v_fma_f32 v178, v19, v181, v243
	s_mov_b32 s2, 0x8000
	v_mul_f32_e32 v177, v178, v177
	v_add_co_u32_e32 v178, vcc, s2, v96
	v_cvt_pk_bf16_f32 v177, v115, v177
	v_lshlrev_b32_e32 v115, 16, v174
	s_nop 0
	v_addc_co_u32_e32 v179, vcc, 0, v97, vcc
	global_store_dwordx2 v[178:179], v[176:177], off offset:1024
	v_fma_f32 v176, v12, v182, v243
	v_mul_f32_e32 v115, v176, v115
	v_and_b32_e32 v174, 0xffff0000, v174
	v_fma_f32 v176, v13, v183, v243
	s_waitcnt lgkmcnt(1)
	v_mfma_f32_16x16x32_bf16 v[224:227], v[224:227], v[92:95], 0
	v_mul_f32_e32 v174, v176, v174
	v_cvt_pk_bf16_f32 v174, v115, v174
	v_lshlrev_b32_e32 v115, 16, v175
	v_fma_f32 v176, v14, v184, v243
	v_mul_f32_e32 v115, v176, v115
	v_and_b32_e32 v175, 0xffff0000, v175
	v_fma_f32 v176, v15, v185, v243
	v_mul_f32_e32 v175, v176, v175
	v_cvt_pk_bf16_f32 v175, v115, v175
	global_store_dwordx2 v[98:99], v[174:175], off offset:32
	v_lshlrev_b32_e32 v115, 16, v172
	v_fma_f32 v174, v8, v224, v243
	v_mul_f32_e32 v115, v174, v115
	v_and_b32_e32 v172, 0xffff0000, v172
	v_fma_f32 v174, v9, v225, v243
	s_waitcnt lgkmcnt(0)
	v_mfma_f32_16x16x32_bf16 v[92:95], v[228:231], v[92:95], 0
	v_mul_f32_e32 v172, v174, v172
	v_cvt_pk_bf16_f32 v172, v115, v172
	v_lshlrev_b32_e32 v115, 16, v173
	v_fma_f32 v174, v10, v226, v243
	v_mul_f32_e32 v115, v174, v115
	v_and_b32_e32 v173, 0xffff0000, v173
	v_fma_f32 v174, v11, v227, v243
	v_mul_f32_e32 v173, v174, v173
	v_cvt_pk_bf16_f32 v173, v115, v173
	v_lshlrev_b32_e32 v115, 16, v170
	v_fma_f32 v92, v4, v92, v243
	v_mul_f32_e32 v92, v92, v115
	v_and_b32_e32 v115, 0xffff0000, v170
	v_fma_f32 v93, v5, v93, v243
	v_mul_f32_e32 v93, v93, v115
	global_store_dwordx2 v[98:99], v[172:173], off offset:64
	v_cvt_pk_bf16_f32 v92, v92, v93
	v_lshlrev_b32_e32 v93, 16, v171
	v_fma_f32 v94, v6, v94, v243
	v_mul_f32_e32 v93, v94, v93
	v_and_b32_e32 v94, 0xffff0000, v171
	v_fmac_f32_e32 v243, v7, v95
	v_mul_f32_e32 v94, v243, v94
	v_cvt_pk_bf16_f32 v93, v93, v94
	global_store_dwordx2 v[98:99], v[92:93], off offset:96
	ds_read_b128 v[92:95], v113 offset:4096
	ds_read_b128 v[170:173], v113 offset:8448
	ds_read_b128 v[174:177], v113 offset:12800
	ds_read_b128 v[178:181], v113 offset:17152
	s_waitcnt vmcnt(55) lgkmcnt(3)
	v_mfma_f32_16x16x32_bf16 v[92:95], v[92:95], v[88:91], 0
	s_mov_b64 s[2:3], 0x10400
	s_waitcnt lgkmcnt(2)
	v_mfma_f32_16x16x32_bf16 v[170:173], v[170:173], v[88:91], 0
	s_waitcnt lgkmcnt(1)
	v_mfma_f32_16x16x32_bf16 v[174:177], v[174:177], v[88:91], 0
	s_waitcnt lgkmcnt(0)
	v_mfma_f32_16x16x32_bf16 v[88:91], v[178:181], v[88:91], 0
	ds_read_b128 v[178:181], v113 offset:4160
	s_waitcnt vmcnt(54) lgkmcnt(0)
	v_mfma_f32_16x16x32_bf16 v[92:95], v[178:181], v[84:87], v[92:95]
	ds_read_b128 v[178:181], v113 offset:8512
	s_waitcnt lgkmcnt(0)
; __device__ __forceinline__ unsigned cvt_pk_bf16(float lo, float hi) { unsigned r; asm volatile("v_cvt_pk_bf16_f32 %0, %1, %2" : "=v"(r) : "v"(lo), "v"(hi)); return r; }
; __device__ __forceinline__ float bflo(unsigned u) { return __uint_as_float(u << 16); }
; __device__ __forceinline__ float bfhi(unsigned u) { return __uint_as_float(u & 0xffff0000u); }
; #define LAS __attribute__((address_space(3)))
; __device__ __forceinline__ void sgu_item(LAS unsigned char* lds, const bf16* P, bf16* Y, const float* gain, const bf16* Wsb, const float* bs, int item, int tid) {
;     ...
; #pragma unroll
;     for (int ib = 0; ib < 8; ++ib) {
;         f32x4 acc[4];
; #pragma unroll
;         for (int db = 0; db < 4; ++db) acc[db] = (f32x4){0.f, 0.f, 0.f, 0.f};
; #pragma unroll
;         for (int ks = 0; ks < 4; ++ks) if (ks <= (ib >> 1)) {
; #pragma unroll
;             for (int db = 0; db < 4; ++db) { const bf16x8 vf = *(const LAS bf16x8*)(Vt + (16 * db + fr) * 136 + 32 * ks + 8 * fq); acc[db] = __builtin_amdgcn_mfma_f32_16x16x32_bf16(vf, wfr[ib][ks], acc[db], 0, 0, 0); } }
;         bf16* yp = Y + (size_t)(R0 + 16 * ib + fr) * D + 512 + g * 64 + 4 * fq; const float bias = bia[ib];
; #pragma unroll
;         for (int db = 0; db < 4; ++db) {
;             v2u wv; wv.x = cvt_pk_bf16(bflo(sur[ib][db].x) * (acc[db][0] * gn[db][0] + bias), bfhi(sur[ib][db].x) * (acc[db][1] * gn[db][1] + bias));
;             wv.y = cvt_pk_bf16(bflo(sur[ib][db].y) * (acc[db][2] * gn[db][2] + bias), bfhi(sur[ib][db].y) * (acc[db][3] * gn[db][3] + bias));
;             *(v2u*)(yp + 16 * db) = wv; }
	v_mfma_f32_16x16x32_bf16 v[170:173], v[178:181], v[84:87], v[170:173]
	ds_read_b128 v[178:181], v113 offset:12864
	s_waitcnt lgkmcnt(0)
	v_mfma_f32_16x16x32_bf16 v[174:177], v[178:181], v[84:87], v[174:177]
	ds_read_b128 v[178:181], v113 offset:17216
	s_waitcnt lgkmcnt(0)
	v_mfma_f32_16x16x32_bf16 v[84:87], v[178:181], v[84:87], v[88:91]
	s_waitcnt vmcnt(53)
	s_nop 1
	v_lshlrev_b32_e32 v90, 16, v168
	s_waitcnt vmcnt(49)
	v_fma_f32 v91, v16, v92, v223
	v_mul_f32_e32 v90, v91, v90
	v_and_b32_e32 v91, 0xffff0000, v168
	v_fma_f32 v92, v17, v93, v223
	v_mul_f32_e32 v91, v92, v91
	v_cvt_pk_bf16_f32 v90, v90, v91
	v_lshlrev_b32_e32 v91, 16, v169
	v_fma_f32 v92, v18, v94, v223
	v_mul_f32_e32 v91, v92, v91
	v_and_b32_e32 v92, 0xffff0000, v169
	v_fma_f32 v93, v19, v95, v223
	v_lshl_add_u64 v[88:89], v[96:97], 0, s[2:3]
	v_mul_f32_e32 v92, v93, v92
	s_mov_b32 s2, 0x10000
	v_cvt_pk_bf16_f32 v91, v91, v92
	v_add_co_u32_e32 v92, vcc, s2, v96
	v_fma_f32 v84, v4, v84, v223
	s_nop 0
	v_addc_co_u32_e32 v93, vcc, 0, v97, vcc
	global_store_dwordx2 v[92:93], v[90:91], off offset:1024
	v_lshlrev_b32_e32 v90, 16, v166
	v_fma_f32 v91, v12, v170, v223
	v_mul_f32_e32 v90, v91, v90
	v_and_b32_e32 v91, 0xffff0000, v166
	v_fma_f32 v92, v13, v171, v223
	v_mul_f32_e32 v91, v92, v91
	v_cvt_pk_bf16_f32 v90, v90, v91
	v_lshlrev_b32_e32 v91, 16, v167
	v_fma_f32 v92, v14, v172, v223
	v_mul_f32_e32 v91, v92, v91
	v_and_b32_e32 v92, 0xffff0000, v167
	v_fma_f32 v93, v15, v173, v223
	v_mul_f32_e32 v92, v93, v92
	v_cvt_pk_bf16_f32 v91, v91, v92
	global_store_dwordx2 v[88:89], v[90:91], off offset:32
	v_lshlrev_b32_e32 v90, 16, v164
	v_fma_f32 v91, v8, v174, v223
	v_mul_f32_e32 v90, v91, v90
	v_and_b32_e32 v91, 0xffff0000, v164
	v_fma_f32 v92, v9, v175, v223
	v_mul_f32_e32 v91, v92, v91
	v_cvt_pk_bf16_f32 v90, v90, v91
	v_lshlrev_b32_e32 v91, 16, v165
	v_fma_f32 v92, v10, v176, v223
	v_mul_f32_e32 v91, v92, v91
	v_and_b32_e32 v92, 0xffff0000, v165
	v_fma_f32 v93, v11, v177, v223
	v_mul_f32_e32 v92, v93, v92
	v_cvt_pk_bf16_f32 v91, v91, v92
	global_store_dwordx2 v[88:89], v[90:91], off offset:64
	v_lshlrev_b32_e32 v90, 16, v162
	v_mul_f32_e32 v84, v84, v90
	v_and_b32_e32 v90, 0xffff0000, v162
	v_fma_f32 v85, v5, v85, v223
	v_mul_f32_e32 v85, v85, v90
	v_cvt_pk_bf16_f32 v84, v84, v85
	v_lshlrev_b32_e32 v85, 16, v163
	v_fma_f32 v86, v6, v86, v223
	v_mul_f32_e32 v85, v86, v85
	v_and_b32_e32 v86, 0xffff0000, v163
	v_fmac_f32_e32 v223, v7, v87
	v_mul_f32_e32 v86, v223, v86
	v_cvt_pk_bf16_f32 v85, v85, v86
	global_store_dwordx2 v[88:89], v[84:85], off offset:96
	ds_read_b128 v[84:87], v113 offset:4096
	ds_read_b128 v[88:91], v113 offset:8448
	ds_read_b128 v[92:95], v113 offset:12800
	ds_read_b128 v[162:165], v113 offset:17152
	s_waitcnt vmcnt(52) lgkmcnt(3)
	v_mfma_f32_16x16x32_bf16 v[84:87], v[84:87], v[80:83], 0
	s_mov_b64 s[2:3], 0x18400
	s_waitcnt lgkmcnt(2)
	v_mfma_f32_16x16x32_bf16 v[88:91], v[88:91], v[80:83], 0
	s_waitcnt lgkmcnt(1)
	v_mfma_f32_16x16x32_bf16 v[92:95], v[92:95], v[80:83], 0
	s_waitcnt lgkmcnt(0)
	v_mfma_f32_16x16x32_bf16 v[80:83], v[162:165], v[80:83], 0
	ds_read_b128 v[162:165], v113 offset:4160
	s_waitcnt vmcnt(51) lgkmcnt(0)
	v_mfma_f32_16x16x32_bf16 v[84:87], v[162:165], v[76:79], v[84:87]
	ds_read_b128 v[162:165], v113 offset:8512
	s_waitcnt lgkmcnt(0)
	v_mfma_f32_16x16x32_bf16 v[88:91], v[162:165], v[76:79], v[88:91]
	ds_read_b128 v[162:165], v113 offset:12864
	s_waitcnt lgkmcnt(0)
	v_mfma_f32_16x16x32_bf16 v[92:95], v[162:165], v[76:79], v[92:95]
	ds_read_b128 v[162:165], v113 offset:17216
	s_waitcnt lgkmcnt(0)
	v_mfma_f32_16x16x32_bf16 v[76:79], v[162:165], v[76:79], v[80:83]
	s_waitcnt vmcnt(50)
	s_nop 1
	v_lshlrev_b32_e32 v82, 16, v160
	s_waitcnt vmcnt(46)
	v_fma_f32 v83, v16, v84, v123
	v_mul_f32_e32 v82, v83, v82
	v_and_b32_e32 v83, 0xffff0000, v160
	v_fma_f32 v84, v17, v85, v123
	v_mul_f32_e32 v83, v84, v83
	v_cvt_pk_bf16_f32 v82, v82, v83
	v_lshlrev_b32_e32 v83, 16, v161
	v_fma_f32 v84, v18, v86, v123
	v_mul_f32_e32 v83, v84, v83
	v_and_b32_e32 v84, 0xffff0000, v161
	v_fma_f32 v85, v19, v87, v123
	v_lshl_add_u64 v[80:81], v[96:97], 0, s[2:3]
	v_mul_f32_e32 v84, v85, v84
	s_mov_b32 s2, 0x18000
	v_cvt_pk_bf16_f32 v83, v83, v84
	v_add_co_u32_e32 v84, vcc, s2, v96
	v_fma_f32 v76, v4, v76, v123
	s_nop 0
	v_addc_co_u32_e32 v85, vcc, 0, v97, vcc
	global_store_dwordx2 v[84:85], v[82:83], off offset:1024
	v_lshlrev_b32_e32 v82, 16, v158
	v_fma_f32 v83, v12, v88, v123
	v_mul_f32_e32 v82, v83, v82
	v_and_b32_e32 v83, 0xffff0000, v158
	v_fma_f32 v84, v13, v89, v123
	v_mul_f32_e32 v83, v84, v83
	v_cvt_pk_bf16_f32 v82, v82, v83
	v_lshlrev_b32_e32 v83, 16, v159
	v_fma_f32 v84, v14, v90, v123
	v_mul_f32_e32 v83, v84, v83
	v_and_b32_e32 v84, 0xffff0000, v159
	v_fma_f32 v85, v15, v91, v123
	v_mul_f32_e32 v84, v85, v84
	v_cvt_pk_bf16_f32 v83, v83, v84
	global_store_dwordx2 v[80:81], v[82:83], off offset:32
	v_lshlrev_b32_e32 v82, 16, v156
	v_fma_f32 v83, v8, v92, v123
	v_mul_f32_e32 v82, v83, v82
	v_and_b32_e32 v83, 0xffff0000, v156
	v_fma_f32 v84, v9, v93, v123
	v_mul_f32_e32 v83, v84, v83
	v_cvt_pk_bf16_f32 v82, v82, v83
	v_lshlrev_b32_e32 v83, 16, v157
	v_fma_f32 v84, v10, v94, v123
	v_mul_f32_e32 v83, v84, v83
	v_and_b32_e32 v84, 0xffff0000, v157
	v_fma_f32 v85, v11, v95, v123
	v_mul_f32_e32 v84, v85, v84
	v_cvt_pk_bf16_f32 v83, v83, v84
	global_store_dwordx2 v[80:81], v[82:83], off offset:64
	v_lshlrev_b32_e32 v82, 16, v154
	v_mul_f32_e32 v76, v76, v82
	v_and_b32_e32 v82, 0xffff0000, v154
	v_fma_f32 v77, v5, v77, v123
	v_mul_f32_e32 v77, v77, v82
	v_cvt_pk_bf16_f32 v76, v76, v77
	v_lshlrev_b32_e32 v77, 16, v155
	v_fma_f32 v78, v6, v78, v123
	v_mul_f32_e32 v77, v78, v77
	v_and_b32_e32 v78, 0xffff0000, v155
	v_fmac_f32_e32 v123, v7, v79
	v_mul_f32_e32 v78, v123, v78
	v_cvt_pk_bf16_f32 v77, v77, v78
	global_store_dwordx2 v[80:81], v[76:77], off offset:96
	ds_read_b128 v[76:79], v113 offset:4096
	ds_read_b128 v[80:83], v113 offset:8448
	ds_read_b128 v[84:87], v113 offset:12800
	ds_read_b128 v[88:91], v113 offset:17152
	s_waitcnt vmcnt(49) lgkmcnt(3)
; __device__ __forceinline__ unsigned cvt_pk_bf16(float lo, float hi) { unsigned r; asm volatile("v_cvt_pk_bf16_f32 %0, %1, %2" : "=v"(r) : "v"(lo), "v"(hi)); return r; }
; __device__ __forceinline__ float bflo(unsigned u) { return __uint_as_float(u << 16); }
; __device__ __forceinline__ float bfhi(unsigned u) { return __uint_as_float(u & 0xffff0000u); }
; #define LAS __attribute__((address_space(3)))
; __device__ __forceinline__ void sgu_item(LAS unsigned char* lds, const bf16* P, bf16* Y, const float* gain, const bf16* Wsb, const float* bs, int item, int tid) {
;     ...
; #pragma unroll
;     for (int ib = 0; ib < 8; ++ib) {
;         f32x4 acc[4];
; #pragma unroll
;         for (int db = 0; db < 4; ++db) acc[db] = (f32x4){0.f, 0.f, 0.f, 0.f};
; #pragma unroll
;         for (int ks = 0; ks < 4; ++ks) if (ks <= (ib >> 1)) {
; #pragma unroll
;             for (int db = 0; db < 4; ++db) { const bf16x8 vf = *(const LAS bf16x8*)(Vt + (16 * db + fr) * 136 + 32 * ks + 8 * fq); acc[db] = __builtin_amdgcn_mfma_f32_16x16x32_bf16(vf, wfr[ib][ks], acc[db], 0, 0, 0); } }
;         bf16* yp = Y + (size_t)(R0 + 16 * ib + fr) * D + 512 + g * 64 + 4 * fq; const float bias = bia[ib];
; #pragma unroll
;         for (int db = 0; db < 4; ++db) {
;             v2u wv; wv.x = cvt_pk_bf16(bflo(sur[ib][db].x) * (acc[db][0] * gn[db][0] + bias), bfhi(sur[ib][db].x) * (acc[db][1] * gn[db][1] + bias));
;             wv.y = cvt_pk_bf16(bflo(sur[ib][db].y) * (acc[db][2] * gn[db][2] + bias), bfhi(sur[ib][db].y) * (acc[db][3] * gn[db][3] + bias));
;             *(v2u*)(yp + 16 * db) = wv; }
	v_mfma_f32_16x16x32_bf16 v[76:79], v[76:79], v[72:75], 0
	s_mov_b64 s[2:3], 0x20400
	s_waitcnt lgkmcnt(2)
	v_mfma_f32_16x16x32_bf16 v[80:83], v[80:83], v[72:75], 0
	s_waitcnt lgkmcnt(1)
	v_mfma_f32_16x16x32_bf16 v[84:87], v[84:87], v[72:75], 0
	s_waitcnt lgkmcnt(0)
	v_mfma_f32_16x16x32_bf16 v[72:75], v[88:91], v[72:75], 0
	ds_read_b128 v[88:91], v113 offset:4160
	s_waitcnt vmcnt(48) lgkmcnt(0)
	v_mfma_f32_16x16x32_bf16 v[76:79], v[88:91], v[68:71], v[76:79]
	ds_read_b128 v[88:91], v113 offset:8512
	s_waitcnt lgkmcnt(0)
	v_mfma_f32_16x16x32_bf16 v[80:83], v[88:91], v[68:71], v[80:83]
	ds_read_b128 v[88:91], v113 offset:12864
	s_waitcnt lgkmcnt(0)
	v_mfma_f32_16x16x32_bf16 v[84:87], v[88:91], v[68:71], v[84:87]
	ds_read_b128 v[88:91], v113 offset:17216
	s_waitcnt lgkmcnt(0)
	v_mfma_f32_16x16x32_bf16 v[68:71], v[88:91], v[68:71], v[72:75]
	s_nop 2
	ds_read_b128 v[72:75], v113 offset:4224
	s_waitcnt vmcnt(47) lgkmcnt(0)
	v_mfma_f32_16x16x32_bf16 v[72:75], v[72:75], v[64:67], v[76:79]
	s_nop 2
	ds_read_b128 v[76:79], v113 offset:8576
	s_waitcnt lgkmcnt(0)
	v_mfma_f32_16x16x32_bf16 v[76:79], v[76:79], v[64:67], v[80:83]
	s_nop 2
	ds_read_b128 v[80:83], v113 offset:12928
	s_waitcnt lgkmcnt(0)
	v_mfma_f32_16x16x32_bf16 v[80:83], v[80:83], v[64:67], v[84:87]
	s_nop 2
	ds_read_b128 v[84:87], v113 offset:17280
	s_waitcnt lgkmcnt(0)
	v_mfma_f32_16x16x32_bf16 v[64:67], v[84:87], v[64:67], v[68:71]
	s_waitcnt vmcnt(46)
	s_nop 1
	v_lshlrev_b32_e32 v70, 16, v152
	s_waitcnt vmcnt(42)
	v_fma_f32 v71, v16, v72, v121
	v_mul_f32_e32 v70, v71, v70
	v_and_b32_e32 v71, 0xffff0000, v152
	v_fma_f32 v72, v17, v73, v121
	v_mul_f32_e32 v71, v72, v71
	v_cvt_pk_bf16_f32 v70, v70, v71
	v_lshlrev_b32_e32 v71, 16, v153
	v_fma_f32 v72, v18, v74, v121
	v_mul_f32_e32 v71, v72, v71
	v_and_b32_e32 v72, 0xffff0000, v153
	v_fma_f32 v73, v19, v75, v121
	v_lshl_add_u64 v[68:69], v[96:97], 0, s[2:3]
	v_mul_f32_e32 v72, v73, v72
	s_mov_b32 s2, 0x20000
	v_cvt_pk_bf16_f32 v71, v71, v72
	v_add_co_u32_e32 v72, vcc, s2, v96
	v_fma_f32 v64, v4, v64, v121
	s_nop 0
	v_addc_co_u32_e32 v73, vcc, 0, v97, vcc
	global_store_dwordx2 v[72:73], v[70:71], off offset:1024
	v_lshlrev_b32_e32 v70, 16, v150
	v_fma_f32 v71, v12, v76, v121
	v_mul_f32_e32 v70, v71, v70
	v_and_b32_e32 v71, 0xffff0000, v150
	v_fma_f32 v72, v13, v77, v121
	v_mul_f32_e32 v71, v72, v71
	v_cvt_pk_bf16_f32 v70, v70, v71
	v_lshlrev_b32_e32 v71, 16, v151
	v_fma_f32 v72, v14, v78, v121
	v_mul_f32_e32 v71, v72, v71
	v_and_b32_e32 v72, 0xffff0000, v151
	v_fma_f32 v73, v15, v79, v121
	v_mul_f32_e32 v72, v73, v72
	v_cvt_pk_bf16_f32 v71, v71, v72
	global_store_dwordx2 v[68:69], v[70:71], off offset:32
	v_lshlrev_b32_e32 v70, 16, v148
	v_fma_f32 v71, v8, v80, v121
	v_mul_f32_e32 v70, v71, v70
	v_and_b32_e32 v71, 0xffff0000, v148
	v_fma_f32 v72, v9, v81, v121
	v_mul_f32_e32 v71, v72, v71
	v_cvt_pk_bf16_f32 v70, v70, v71
	v_lshlrev_b32_e32 v71, 16, v149
	v_fma_f32 v72, v10, v82, v121
	v_mul_f32_e32 v71, v72, v71
	v_and_b32_e32 v72, 0xffff0000, v149
	v_fma_f32 v73, v11, v83, v121
	v_mul_f32_e32 v72, v73, v72
	v_cvt_pk_bf16_f32 v71, v71, v72
	global_store_dwordx2 v[68:69], v[70:71], off offset:64
	v_lshlrev_b32_e32 v70, 16, v146
	v_mul_f32_e32 v64, v64, v70
	v_and_b32_e32 v70, 0xffff0000, v146
	v_fma_f32 v65, v5, v65, v121
	v_mul_f32_e32 v65, v65, v70
	v_cvt_pk_bf16_f32 v64, v64, v65
	v_lshlrev_b32_e32 v65, 16, v147
	v_fma_f32 v66, v6, v66, v121
	v_mul_f32_e32 v65, v66, v65
	v_and_b32_e32 v66, 0xffff0000, v147
	v_fmac_f32_e32 v121, v7, v67
	v_mul_f32_e32 v66, v121, v66
	v_cvt_pk_bf16_f32 v65, v65, v66
	global_store_dwordx2 v[68:69], v[64:65], off offset:96
	ds_read_b128 v[64:67], v113 offset:4096
	ds_read_b128 v[68:71], v113 offset:8448
	ds_read_b128 v[72:75], v113 offset:12800
	ds_read_b128 v[76:79], v113 offset:17152
	s_waitcnt vmcnt(45) lgkmcnt(3)
	v_mfma_f32_16x16x32_bf16 v[64:67], v[64:67], v[60:63], 0
	s_mov_b64 s[2:3], 0x28400
	s_waitcnt lgkmcnt(2)
	v_mfma_f32_16x16x32_bf16 v[68:71], v[68:71], v[60:63], 0
	s_waitcnt lgkmcnt(1)
	v_mfma_f32_16x16x32_bf16 v[72:75], v[72:75], v[60:63], 0
	s_waitcnt lgkmcnt(0)
	v_mfma_f32_16x16x32_bf16 v[60:63], v[76:79], v[60:63], 0
	ds_read_b128 v[76:79], v113 offset:4160
	s_waitcnt vmcnt(44) lgkmcnt(0)
	v_mfma_f32_16x16x32_bf16 v[64:67], v[76:79], v[56:59], v[64:67]
	ds_read_b128 v[76:79], v113 offset:8512
	s_waitcnt lgkmcnt(0)
	v_mfma_f32_16x16x32_bf16 v[68:71], v[76:79], v[56:59], v[68:71]
	ds_read_b128 v[76:79], v113 offset:12864
	s_waitcnt lgkmcnt(0)
	v_mfma_f32_16x16x32_bf16 v[72:75], v[76:79], v[56:59], v[72:75]
	ds_read_b128 v[76:79], v113 offset:17216
	s_waitcnt lgkmcnt(0)
	v_mfma_f32_16x16x32_bf16 v[56:59], v[76:79], v[56:59], v[60:63]
	s_nop 2
	ds_read_b128 v[60:63], v113 offset:4224
	s_waitcnt vmcnt(43) lgkmcnt(0)
	v_mfma_f32_16x16x32_bf16 v[60:63], v[60:63], v[52:55], v[64:67]
	s_nop 2
	ds_read_b128 v[64:67], v113 offset:8576
	s_waitcnt lgkmcnt(0)
	v_mfma_f32_16x16x32_bf16 v[64:67], v[64:67], v[52:55], v[68:71]
	s_nop 2
	ds_read_b128 v[68:71], v113 offset:12928
	s_waitcnt lgkmcnt(0)
	v_mfma_f32_16x16x32_bf16 v[68:71], v[68:71], v[52:55], v[72:75]
	s_nop 2
	ds_read_b128 v[72:75], v113 offset:17280
	s_waitcnt lgkmcnt(0)
	v_mfma_f32_16x16x32_bf16 v[52:55], v[72:75], v[52:55], v[56:59]
	s_waitcnt vmcnt(42)
	s_nop 1
	v_lshlrev_b32_e32 v58, 16, v144
	s_waitcnt vmcnt(38)
; __device__ __forceinline__ unsigned cvt_pk_bf16(float lo, float hi) { unsigned r; asm volatile("v_cvt_pk_bf16_f32 %0, %1, %2" : "=v"(r) : "v"(lo), "v"(hi)); return r; }
; __device__ __forceinline__ float bflo(unsigned u) { return __uint_as_float(u << 16); }
; __device__ __forceinline__ float bfhi(unsigned u) { return __uint_as_float(u & 0xffff0000u); }
; #define LAS __attribute__((address_space(3)))
; __device__ __forceinline__ void sgu_item(LAS unsigned char* lds, const bf16* P, bf16* Y, const float* gain, const bf16* Wsb, const float* bs, int item, int tid) {
;     ...
; #pragma unroll
;     for (int ib = 0; ib < 8; ++ib) {
;         f32x4 acc[4];
; #pragma unroll
;         for (int db = 0; db < 4; ++db) acc[db] = (f32x4){0.f, 0.f, 0.f, 0.f};
; #pragma unroll
;         for (int ks = 0; ks < 4; ++ks) if (ks <= (ib >> 1)) {
; #pragma unroll
;             for (int db = 0; db < 4; ++db) { const bf16x8 vf = *(const LAS bf16x8*)(Vt + (16 * db + fr) * 136 + 32 * ks + 8 * fq); acc[db] = __builtin_amdgcn_mfma_f32_16x16x32_bf16(vf, wfr[ib][ks], acc[db], 0, 0, 0); } }
;         bf16* yp = Y + (size_t)(R0 + 16 * ib + fr) * D + 512 + g * 64 + 4 * fq; const float bias = bia[ib];
; #pragma unroll
;         for (int db = 0; db < 4; ++db) {
;             v2u wv; wv.x = cvt_pk_bf16(bflo(sur[ib][db].x) * (acc[db][0] * gn[db][0] + bias), bfhi(sur[ib][db].x) * (acc[db][1] * gn[db][1] + bias));
;             wv.y = cvt_pk_bf16(bflo(sur[ib][db].y) * (acc[db][2] * gn[db][2] + bias), bfhi(sur[ib][db].y) * (acc[db][3] * gn[db][3] + bias));
;             *(v2u*)(yp + 16 * db) = wv; }
	v_fma_f32 v59, v16, v60, v119
	v_mul_f32_e32 v58, v59, v58
	v_and_b32_e32 v59, 0xffff0000, v144
	v_fma_f32 v60, v17, v61, v119
	v_mul_f32_e32 v59, v60, v59
	v_cvt_pk_bf16_f32 v58, v58, v59
	v_lshlrev_b32_e32 v59, 16, v145
	v_fma_f32 v60, v18, v62, v119
	v_mul_f32_e32 v59, v60, v59
	v_and_b32_e32 v60, 0xffff0000, v145
	v_fma_f32 v61, v19, v63, v119
	v_lshl_add_u64 v[56:57], v[96:97], 0, s[2:3]
	v_mul_f32_e32 v60, v61, v60
	s_mov_b32 s2, 0x28000
	v_cvt_pk_bf16_f32 v59, v59, v60
	v_add_co_u32_e32 v60, vcc, s2, v96
	v_fma_f32 v52, v4, v52, v119
	s_nop 0
	v_addc_co_u32_e32 v61, vcc, 0, v97, vcc
	global_store_dwordx2 v[60:61], v[58:59], off offset:1024
	v_lshlrev_b32_e32 v58, 16, v142
	v_fma_f32 v59, v12, v64, v119
	v_mul_f32_e32 v58, v59, v58
	v_and_b32_e32 v59, 0xffff0000, v142
	v_fma_f32 v60, v13, v65, v119
	v_mul_f32_e32 v59, v60, v59
	v_cvt_pk_bf16_f32 v58, v58, v59
	v_lshlrev_b32_e32 v59, 16, v143
	v_fma_f32 v60, v14, v66, v119
	v_mul_f32_e32 v59, v60, v59
	v_and_b32_e32 v60, 0xffff0000, v143
	v_fma_f32 v61, v15, v67, v119
	v_mul_f32_e32 v60, v61, v60
	v_cvt_pk_bf16_f32 v59, v59, v60
	global_store_dwordx2 v[56:57], v[58:59], off offset:32
	v_lshlrev_b32_e32 v58, 16, v140
	v_fma_f32 v59, v8, v68, v119
	v_mul_f32_e32 v58, v59, v58
	v_and_b32_e32 v59, 0xffff0000, v140
	v_fma_f32 v60, v9, v69, v119
	v_mul_f32_e32 v59, v60, v59
	v_cvt_pk_bf16_f32 v58, v58, v59
	v_lshlrev_b32_e32 v59, 16, v141
	v_fma_f32 v60, v10, v70, v119
	v_mul_f32_e32 v59, v60, v59
	v_and_b32_e32 v60, 0xffff0000, v141
	v_fma_f32 v61, v11, v71, v119
	v_mul_f32_e32 v60, v61, v60
	v_cvt_pk_bf16_f32 v59, v59, v60
	global_store_dwordx2 v[56:57], v[58:59], off offset:64
	v_lshlrev_b32_e32 v58, 16, v138
	v_mul_f32_e32 v52, v52, v58
	v_and_b32_e32 v58, 0xffff0000, v138
	v_fma_f32 v53, v5, v53, v119
	v_mul_f32_e32 v53, v53, v58
	v_cvt_pk_bf16_f32 v52, v52, v53
	v_lshlrev_b32_e32 v53, 16, v139
	v_fma_f32 v54, v6, v54, v119
	v_mul_f32_e32 v53, v54, v53
	v_and_b32_e32 v54, 0xffff0000, v139
	v_fmac_f32_e32 v119, v7, v55
	v_mul_f32_e32 v54, v119, v54
	v_cvt_pk_bf16_f32 v53, v53, v54
	global_store_dwordx2 v[56:57], v[52:53], off offset:96
	ds_read_b128 v[52:55], v113 offset:4096
	ds_read_b128 v[56:59], v113 offset:8448
	ds_read_b128 v[60:63], v113 offset:12800
	ds_read_b128 v[64:67], v113 offset:17152
	s_waitcnt vmcnt(41) lgkmcnt(3)
	v_mfma_f32_16x16x32_bf16 v[52:55], v[52:55], v[48:51], 0
	s_mov_b64 s[2:3], 0x30400
	s_waitcnt lgkmcnt(2)
	v_mfma_f32_16x16x32_bf16 v[56:59], v[56:59], v[48:51], 0
	s_waitcnt lgkmcnt(1)
	v_mfma_f32_16x16x32_bf16 v[60:63], v[60:63], v[48:51], 0
	s_waitcnt lgkmcnt(0)
	v_mfma_f32_16x16x32_bf16 v[48:51], v[64:67], v[48:51], 0
	ds_read_b128 v[64:67], v113 offset:4160
	s_waitcnt vmcnt(40) lgkmcnt(0)
	v_mfma_f32_16x16x32_bf16 v[52:55], v[64:67], v[44:47], v[52:55]
	ds_read_b128 v[64:67], v113 offset:8512
	s_waitcnt lgkmcnt(0)
	v_mfma_f32_16x16x32_bf16 v[56:59], v[64:67], v[44:47], v[56:59]
	ds_read_b128 v[64:67], v113 offset:12864
	s_waitcnt lgkmcnt(0)
	v_mfma_f32_16x16x32_bf16 v[60:63], v[64:67], v[44:47], v[60:63]
	ds_read_b128 v[64:67], v113 offset:17216
	s_waitcnt lgkmcnt(0)
	v_mfma_f32_16x16x32_bf16 v[44:47], v[64:67], v[44:47], v[48:51]
	s_nop 2
	ds_read_b128 v[48:51], v113 offset:4224
	s_waitcnt vmcnt(39) lgkmcnt(0)
	v_mfma_f32_16x16x32_bf16 v[48:51], v[48:51], v[40:43], v[52:55]
	s_nop 2
	ds_read_b128 v[52:55], v113 offset:8576
	s_waitcnt lgkmcnt(0)
	v_mfma_f32_16x16x32_bf16 v[52:55], v[52:55], v[40:43], v[56:59]
	s_nop 2
	ds_read_b128 v[56:59], v113 offset:12928
	s_waitcnt lgkmcnt(0)
	v_mfma_f32_16x16x32_bf16 v[56:59], v[56:59], v[40:43], v[60:63]
	s_nop 2
	ds_read_b128 v[60:63], v113 offset:17280
	s_waitcnt lgkmcnt(0)
	v_mfma_f32_16x16x32_bf16 v[40:43], v[60:63], v[40:43], v[44:47]
	s_nop 2
	ds_read_b128 v[44:47], v113 offset:4288
	s_waitcnt vmcnt(38) lgkmcnt(0)
	v_mfma_f32_16x16x32_bf16 v[44:47], v[44:47], v[36:39], v[48:51]
	s_nop 2
	ds_read_b128 v[48:51], v113 offset:8640
	s_waitcnt lgkmcnt(0)
	v_mfma_f32_16x16x32_bf16 v[48:51], v[48:51], v[36:39], v[52:55]
	s_nop 2
	ds_read_b128 v[52:55], v113 offset:12992
	s_waitcnt lgkmcnt(0)
	v_mfma_f32_16x16x32_bf16 v[52:55], v[52:55], v[36:39], v[56:59]
	s_nop 2
	ds_read_b128 v[56:59], v113 offset:17344
	s_waitcnt lgkmcnt(0)
	v_mfma_f32_16x16x32_bf16 v[36:39], v[56:59], v[36:39], v[40:43]
	s_waitcnt vmcnt(37)
	s_nop 1
	v_lshlrev_b32_e32 v42, 16, v136
	s_waitcnt vmcnt(33)
; __device__ __forceinline__ unsigned cvt_pk_bf16(float lo, float hi) { unsigned r; asm volatile("v_cvt_pk_bf16_f32 %0, %1, %2" : "=v"(r) : "v"(lo), "v"(hi)); return r; }
; __device__ __forceinline__ float bflo(unsigned u) { return __uint_as_float(u << 16); }
; __device__ __forceinline__ float bfhi(unsigned u) { return __uint_as_float(u & 0xffff0000u); }
; #define LAS __attribute__((address_space(3)))
; __device__ __forceinline__ void sgu_item(LAS unsigned char* lds, const bf16* P, bf16* Y, const float* gain, const bf16* Wsb, const float* bs, int item, int tid) {
;     ...
; #pragma unroll
;     for (int ib = 0; ib < 8; ++ib) {
;         f32x4 acc[4];
; #pragma unroll
;         for (int db = 0; db < 4; ++db) acc[db] = (f32x4){0.f, 0.f, 0.f, 0.f};
; #pragma unroll
;         for (int ks = 0; ks < 4; ++ks) if (ks <= (ib >> 1)) {
; #pragma unroll
;             for (int db = 0; db < 4; ++db) { const bf16x8 vf = *(const LAS bf16x8*)(Vt + (16 * db + fr) * 136 + 32 * ks + 8 * fq); acc[db] = __builtin_amdgcn_mfma_f32_16x16x32_bf16(vf, wfr[ib][ks], acc[db], 0, 0, 0); } }
;         bf16* yp = Y + (size_t)(R0 + 16 * ib + fr) * D + 512 + g * 64 + 4 * fq; const float bias = bia[ib];
; #pragma unroll
;         for (int db = 0; db < 4; ++db) {
;             v2u wv; wv.x = cvt_pk_bf16(bflo(sur[ib][db].x) * (acc[db][0] * gn[db][0] + bias), bfhi(sur[ib][db].x) * (acc[db][1] * gn[db][1] + bias));
;             wv.y = cvt_pk_bf16(bflo(sur[ib][db].y) * (acc[db][2] * gn[db][2] + bias), bfhi(sur[ib][db].y) * (acc[db][3] * gn[db][3] + bias));
;             *(v2u*)(yp + 16 * db) = wv; }
;     }
;     __syncthreads();
	v_fma_f32 v43, v16, v44, v117
	v_mul_f32_e32 v42, v43, v42
	v_and_b32_e32 v43, 0xffff0000, v136
	v_fma_f32 v44, v17, v45, v117
	v_mul_f32_e32 v43, v44, v43
	v_cvt_pk_bf16_f32 v42, v42, v43
	v_lshlrev_b32_e32 v43, 16, v137
	v_fma_f32 v44, v18, v46, v117
	v_mul_f32_e32 v43, v44, v43
	v_and_b32_e32 v44, 0xffff0000, v137
	v_fma_f32 v45, v19, v47, v117
	v_lshl_add_u64 v[40:41], v[96:97], 0, s[2:3]
	v_mul_f32_e32 v44, v45, v44
	s_mov_b32 s2, 0x30000
	v_cvt_pk_bf16_f32 v43, v43, v44
	v_add_co_u32_e32 v44, vcc, s2, v96
	v_fma_f32 v36, v4, v36, v117
	s_nop 0
	v_addc_co_u32_e32 v45, vcc, 0, v97, vcc
	global_store_dwordx2 v[44:45], v[42:43], off offset:1024
	v_lshlrev_b32_e32 v42, 16, v134
	v_fma_f32 v43, v12, v48, v117
	v_mul_f32_e32 v42, v43, v42
	v_and_b32_e32 v43, 0xffff0000, v134
	v_fma_f32 v44, v13, v49, v117
	v_mul_f32_e32 v43, v44, v43
	v_cvt_pk_bf16_f32 v42, v42, v43
	v_lshlrev_b32_e32 v43, 16, v135
	v_fma_f32 v44, v14, v50, v117
	v_mul_f32_e32 v43, v44, v43
	v_and_b32_e32 v44, 0xffff0000, v135
	v_fma_f32 v45, v15, v51, v117
	v_mul_f32_e32 v44, v45, v44
	v_cvt_pk_bf16_f32 v43, v43, v44
	global_store_dwordx2 v[40:41], v[42:43], off offset:32
	v_lshlrev_b32_e32 v42, 16, v132
	v_fma_f32 v43, v8, v52, v117
	v_mul_f32_e32 v42, v43, v42
	v_and_b32_e32 v43, 0xffff0000, v132
	v_fma_f32 v44, v9, v53, v117
	v_mul_f32_e32 v43, v44, v43
	v_cvt_pk_bf16_f32 v42, v42, v43
	v_lshlrev_b32_e32 v43, 16, v133
	v_fma_f32 v44, v10, v54, v117
	v_mul_f32_e32 v43, v44, v43
	v_and_b32_e32 v44, 0xffff0000, v133
	v_fma_f32 v45, v11, v55, v117
	v_mul_f32_e32 v44, v45, v44
	v_cvt_pk_bf16_f32 v43, v43, v44
	global_store_dwordx2 v[40:41], v[42:43], off offset:64
	v_lshlrev_b32_e32 v42, 16, v130
	v_mul_f32_e32 v36, v36, v42
	v_and_b32_e32 v42, 0xffff0000, v130
	v_fma_f32 v37, v5, v37, v117
	v_mul_f32_e32 v37, v37, v42
	v_cvt_pk_bf16_f32 v36, v36, v37
	v_lshlrev_b32_e32 v37, 16, v131
	v_fma_f32 v38, v6, v38, v117
	v_mul_f32_e32 v37, v38, v37
	v_and_b32_e32 v38, 0xffff0000, v131
	v_fmac_f32_e32 v117, v7, v39
	v_mul_f32_e32 v38, v117, v38
	v_cvt_pk_bf16_f32 v37, v37, v38
	global_store_dwordx2 v[40:41], v[36:37], off offset:96
	ds_read_b128 v[36:39], v113 offset:4096
	ds_read_b128 v[40:43], v113 offset:8448
	ds_read_b128 v[44:47], v113 offset:12800
	ds_read_b128 v[48:51], v113 offset:17152
	s_waitcnt vmcnt(36) lgkmcnt(3)
	v_mfma_f32_16x16x32_bf16 v[36:39], v[36:39], v[32:35], 0
	s_mov_b64 s[2:3], 0x38400
	s_waitcnt lgkmcnt(2)
	v_mfma_f32_16x16x32_bf16 v[40:43], v[40:43], v[32:35], 0
	s_waitcnt lgkmcnt(1)
	v_mfma_f32_16x16x32_bf16 v[44:47], v[44:47], v[32:35], 0
	s_waitcnt lgkmcnt(0)
	v_mfma_f32_16x16x32_bf16 v[32:35], v[48:51], v[32:35], 0
	ds_read_b128 v[48:51], v113 offset:4160
	s_waitcnt vmcnt(35) lgkmcnt(0)
	v_mfma_f32_16x16x32_bf16 v[36:39], v[48:51], v[28:31], v[36:39]
	ds_read_b128 v[48:51], v113 offset:8512
	s_waitcnt lgkmcnt(0)
	v_mfma_f32_16x16x32_bf16 v[40:43], v[48:51], v[28:31], v[40:43]
	ds_read_b128 v[48:51], v113 offset:12864
	s_waitcnt lgkmcnt(0)
	v_mfma_f32_16x16x32_bf16 v[44:47], v[48:51], v[28:31], v[44:47]
	ds_read_b128 v[48:51], v113 offset:17216
	s_waitcnt lgkmcnt(0)
	v_mfma_f32_16x16x32_bf16 v[28:31], v[48:51], v[28:31], v[32:35]
	s_nop 2
	ds_read_b128 v[32:35], v113 offset:4224
	s_waitcnt vmcnt(34) lgkmcnt(0)
	v_mfma_f32_16x16x32_bf16 v[32:35], v[32:35], v[24:27], v[36:39]
	s_nop 2
	ds_read_b128 v[36:39], v113 offset:8576
	s_waitcnt lgkmcnt(0)
	v_mfma_f32_16x16x32_bf16 v[36:39], v[36:39], v[24:27], v[40:43]
	s_nop 2
	ds_read_b128 v[40:43], v113 offset:12928
	s_waitcnt lgkmcnt(0)
	v_mfma_f32_16x16x32_bf16 v[40:43], v[40:43], v[24:27], v[44:47]
	s_nop 2
	ds_read_b128 v[44:47], v113 offset:17280
	s_waitcnt lgkmcnt(0)
	v_mfma_f32_16x16x32_bf16 v[24:27], v[44:47], v[24:27], v[28:31]
	s_nop 2
	ds_read_b128 v[28:31], v113 offset:4288
	s_waitcnt vmcnt(33) lgkmcnt(0)
	v_mfma_f32_16x16x32_bf16 v[28:31], v[28:31], v[20:23], v[32:35]
	s_nop 2
	ds_read_b128 v[32:35], v113 offset:8640
	s_waitcnt vmcnt(28)
	s_nop 2
	v_fma_f32 v16, v16, v28, v3
	s_waitcnt lgkmcnt(0)
	v_mfma_f32_16x16x32_bf16 v[32:35], v[32:35], v[20:23], v[36:39]
	s_nop 2
	ds_read_b128 v[36:39], v113 offset:12992
	v_fma_f32 v17, v17, v29, v3
	v_fma_f32 v18, v18, v30, v3
	s_waitcnt lgkmcnt(0)
	v_mfma_f32_16x16x32_bf16 v[36:39], v[36:39], v[20:23], v[40:43]
	s_nop 2
	ds_read_b128 v[40:43], v113 offset:17344
	v_fma_f32 v19, v19, v31, v3
	v_fma_f32 v12, v12, v32, v3
	s_waitcnt lgkmcnt(0)
	v_mfma_f32_16x16x32_bf16 v[20:23], v[40:43], v[20:23], v[24:27]
	s_nop 2
	v_lshlrev_b32_e32 v26, 16, v128
	v_mul_f32_e32 v16, v16, v26
	v_and_b32_e32 v26, 0xffff0000, v128
	v_mul_f32_e32 v17, v17, v26
	v_cvt_pk_bf16_f32 v16, v16, v17
	v_lshlrev_b32_e32 v17, 16, v129
	v_mul_f32_e32 v17, v18, v17
	v_and_b32_e32 v18, 0xffff0000, v129
	v_lshl_add_u64 v[24:25], v[96:97], 0, s[2:3]
	v_mul_f32_e32 v18, v19, v18
	s_mov_b32 s2, 0x38000
	v_cvt_pk_bf16_f32 v17, v17, v18
	v_add_co_u32_e32 v18, vcc, s2, v96
	v_fma_f32 v13, v13, v33, v3
	s_nop 0
	v_addc_co_u32_e32 v19, vcc, 0, v97, vcc
	global_store_dwordx2 v[18:19], v[16:17], off offset:1024
	v_lshlrev_b32_e32 v16, 16, v126
	v_mul_f32_e32 v12, v12, v16
	v_and_b32_e32 v16, 0xffff0000, v126
	v_mul_f32_e32 v13, v13, v16
	v_cvt_pk_bf16_f32 v12, v12, v13
	v_lshlrev_b32_e32 v13, 16, v127
	v_fma_f32 v14, v14, v34, v3
	v_mul_f32_e32 v13, v14, v13
	v_and_b32_e32 v14, 0xffff0000, v127
	v_fma_f32 v15, v15, v35, v3
	v_mul_f32_e32 v14, v15, v14
	v_cvt_pk_bf16_f32 v13, v13, v14
	global_store_dwordx2 v[24:25], v[12:13], off offset:32
	v_lshlrev_b32_e32 v12, 16, v124
	v_fma_f32 v8, v8, v36, v3
	v_mul_f32_e32 v8, v8, v12
	v_and_b32_e32 v12, 0xffff0000, v124
	v_fma_f32 v9, v9, v37, v3
	v_mul_f32_e32 v9, v9, v12
	v_cvt_pk_bf16_f32 v8, v8, v9
	v_lshlrev_b32_e32 v9, 16, v125
	v_fma_f32 v10, v10, v38, v3
	v_mul_f32_e32 v9, v10, v9
	v_and_b32_e32 v10, 0xffff0000, v125
	v_fma_f32 v11, v11, v39, v3
	v_mul_f32_e32 v10, v11, v10
	v_cvt_pk_bf16_f32 v9, v9, v10
	global_store_dwordx2 v[24:25], v[8:9], off offset:64
	v_lshlrev_b32_e32 v8, 16, v0
	v_fma_f32 v4, v4, v20, v3
	v_and_b32_e32 v0, 0xffff0000, v0
	v_fma_f32 v5, v5, v21, v3
	v_mul_f32_e32 v4, v4, v8
	v_mul_f32_e32 v0, v5, v0
	v_cvt_pk_bf16_f32 v0, v4, v0
	v_lshlrev_b32_e32 v4, 16, v1
	v_fma_f32 v5, v6, v22, v3
	v_and_b32_e32 v1, 0xffff0000, v1
	v_fmac_f32_e32 v3, v7, v23
	v_mul_f32_e32 v1, v3, v1
	v_mul_f32_e32 v4, v5, v4
	v_cvt_pk_bf16_f32 v1, v4, v1
	global_store_dwordx2 v[24:25], v[0:1], off offset:96
	s_barrier
